# EpiUp: previous-block halo rows taken with a packed masked multiply (2 per block) instead of four DPP masked copies
# speedup vs baseline: 1.0307x; 1.0026x over previous
;     __device__ __forceinline__ void operator()(const f32x4 (&acc)[2][2][4][2], const Unit& u, int wr, int wc, int fr, int fq) const {
;     ...
;             const int rowb = u.pm * 256 + ai * 128 + wr * 64;
;             const int blk = 4 * u.pm + 2 * ai + wr;
;             float rs[4];
; #pragma unroll
;             for (int m = 0; m < 4; ++m) rs[m] = rsqrtf(SS[rowb + 16 * m + fr] * (1.0f / D) + EPS);
; #pragma unroll
;             for (int n = 0; n < 2; ++n) {
;                 f32x4 cg[4];
; #pragma unroll
;                 for (int bj = 0; bj < 2; ++bj) {
;                     const int oc = (bj ? FF : 0) + 128 * u.pn + 32 * wc + 8 * fq + 4 * n;
;                     const int cgc = 256 * u.pn + 128 * bj + 32 * wc + 8 * fq + 4 * n;
;                     const f32x4 cw0 = *(const f32x4*)(convw + oc), cw1 = *(const f32x4*)(convw + FF2 + oc), cw2 = *(const f32x4*)(convw + 2 * FF2 + oc), cb = *(const f32x4*)(convb + oc);
;                     f32x4 v[4];
; #pragma unroll
;                     for (int m = 0; m < 4; ++m) v[m] = acc[ai][bj][m][n] * rs[m];
.Lfe_begin:
	v_readlane_b32 s13, v236, 19
	s_lshl_b32 s77, s88, 8
	s_lshl_b32 s89, s12, 7
	s_lshl_b32 s75, s88, 2
	s_add_i32 s75, s75, s73
	s_add_i32 s77, s77, s13
	v_add_u32_e32 v246, s77, v153
	v_add_u32_e32 v247, s13, v153
	v_lshlrev_b32_e32 v247, 2, v247
	v_add_u32_e32 v247, 0x22000, v247
	ds_read2_b32 v[238:239], v247 offset0:0 offset1:16
	ds_read2_b32 v[240:241], v247 offset0:32 offset1:48
	ds_read2_b32 v[242:243], v247 offset0:128 offset1:144
	ds_read2_b32 v[244:245], v247 offset0:160 offset1:176
	v_lshlrev_b32_e32 v249, 2, v215
	v_add_u32_e32 v249, 0x21000, v249
	v_add_u32_e32 v248, s89, v215
	v_lshlrev_b32_e32 v237, 2, v248
	v_add_u32_e32 v250, 0x2c00, v237
	ds_read_b128 v[170:173], v249
	ds_read_b128 v[174:177], v249 offset:16
	ds_read_b128 v[178:181], v249 offset:512
	ds_read_b128 v[182:185], v249 offset:528
	ds_read_b128 v[186:189], v249 offset:1024
	ds_read_b128 v[190:193], v249 offset:1040
	ds_read_b128 v[194:197], v249 offset:1536
	ds_read_b128 v[198:201], v249 offset:1552
	v_mul_u32_u24_e32 v151, 0x1600, v246
	v_lshl_add_u32 v151, v248, 1, v151
	v_mov_b32_e32 v219, s64
	v_mov_b32_e32 v220, 0
	v_mov_b32_e32 v221, 0
	v_mov_b32_e32 v222, 0
	v_mov_b32_e32 v223, 0
	v_mov_b32_e32 v224, 0
	v_mov_b32_e32 v225, 0
	v_mov_b32_e32 v226, 0
	v_mov_b32_e32 v227, 0
	v_mov_b32_e32 v228, 0
	v_mov_b32_e32 v229, 0
	v_mov_b32_e32 v230, 0
	v_mov_b32_e32 v231, 0
	v_mov_b32_e32 v232, 0
	v_mov_b32_e32 v233, 0
	v_mov_b32_e32 v234, 0
	v_mov_b32_e32 v235, 0
	s_mul_i32 s56, s75, 0xb000
	s_lshl_b32 s57, s12, 10
	s_add_i32 s56, s56, s57
	v_mul_i32_i24_e32 v150, 0x5800, v216
	v_lshl_add_u32 v150, v215, 2, v150
	v_add_u32_e32 v150, s56, v150
	s_waitcnt lgkmcnt(8)
	v_fmamk_f32 v238, v238, 0x3a800000, v218
	v_fmamk_f32 v239, v239, 0x3a800000, v218
	v_fmamk_f32 v240, v240, 0x3a800000, v218
	v_fmamk_f32 v241, v241, 0x3a800000, v218
	v_fmamk_f32 v242, v242, 0x3a800000, v218
	v_fmamk_f32 v243, v243, 0x3a800000, v218
	v_fmamk_f32 v244, v244, 0x3a800000, v218
	v_fmamk_f32 v245, v245, 0x3a800000, v218
	v_rsq_f32_e32 v238, v238
	v_rsq_f32_e32 v239, v239
	v_rsq_f32_e32 v240, v240
	v_rsq_f32_e32 v241, v241
	v_rsq_f32_e32 v242, v242
	v_rsq_f32_e32 v243, v243
	v_rsq_f32_e32 v244, v244
	v_rsq_f32_e32 v245, v245
	ds_read_b128 v[202:205], v249 offset:2048
	ds_read_b128 v[206:209], v249 offset:2064
	ds_read_b128 v[210:213], v249 offset:2560
	ds_read_b128 v[128:131], v249 offset:2576
	ds_read_b128 v[132:135], v249 offset:3072
	ds_read_b128 v[136:139], v249 offset:3088
	ds_read_b128 v[140:143], v249 offset:3584
	ds_read_b128 v[144:147], v249 offset:3600
	v_pk_mul_f32 v[124:125], v[124:125], v[238:239] op_sel_hi:[1,0]
	v_pk_mul_f32 v[126:127], v[126:127], v[238:239] op_sel_hi:[1,0]
	v_pk_mul_f32 v[92:93], v[92:93], v[238:239] op_sel_hi:[1,0]
	v_pk_mul_f32 v[94:95], v[94:95], v[238:239] op_sel_hi:[1,0]
	v_pk_mul_f32 v[108:109], v[108:109], v[238:239] op_sel_hi:[1,0]
	v_pk_mul_f32 v[110:111], v[110:111], v[238:239] op_sel_hi:[1,0]
	v_pk_mul_f32 v[76:77], v[76:77], v[238:239] op_sel_hi:[1,0]
	v_pk_mul_f32 v[78:79], v[78:79], v[238:239] op_sel_hi:[1,0]
	v_pk_mul_f32 v[120:121], v[120:121], v[238:239] op_sel:[0,1] op_sel_hi:[1,1]
	v_pk_mul_f32 v[122:123], v[122:123], v[238:239] op_sel:[0,1] op_sel_hi:[1,1]
	v_pk_mul_f32 v[88:89], v[88:89], v[238:239] op_sel:[0,1] op_sel_hi:[1,1]
	v_pk_mul_f32 v[90:91], v[90:91], v[238:239] op_sel:[0,1] op_sel_hi:[1,1]
	v_pk_mul_f32 v[104:105], v[104:105], v[238:239] op_sel:[0,1] op_sel_hi:[1,1]
	v_pk_mul_f32 v[106:107], v[106:107], v[238:239] op_sel:[0,1] op_sel_hi:[1,1]
	v_pk_mul_f32 v[72:73], v[72:73], v[238:239] op_sel:[0,1] op_sel_hi:[1,1]
	v_pk_mul_f32 v[74:75], v[74:75], v[238:239] op_sel:[0,1] op_sel_hi:[1,1]
	v_pk_mul_f32 v[116:117], v[116:117], v[240:241] op_sel_hi:[1,0]
	v_pk_mul_f32 v[118:119], v[118:119], v[240:241] op_sel_hi:[1,0]
	v_pk_mul_f32 v[84:85], v[84:85], v[240:241] op_sel_hi:[1,0]
	v_pk_mul_f32 v[86:87], v[86:87], v[240:241] op_sel_hi:[1,0]
	v_pk_mul_f32 v[100:101], v[100:101], v[240:241] op_sel_hi:[1,0]
	v_pk_mul_f32 v[102:103], v[102:103], v[240:241] op_sel_hi:[1,0]
	v_pk_mul_f32 v[68:69], v[68:69], v[240:241] op_sel_hi:[1,0]
	v_pk_mul_f32 v[70:71], v[70:71], v[240:241] op_sel_hi:[1,0]
	v_pk_mul_f32 v[112:113], v[112:113], v[240:241] op_sel:[0,1] op_sel_hi:[1,1]
	v_pk_mul_f32 v[114:115], v[114:115], v[240:241] op_sel:[0,1] op_sel_hi:[1,1]
	v_pk_mul_f32 v[80:81], v[80:81], v[240:241] op_sel:[0,1] op_sel_hi:[1,1]
	v_pk_mul_f32 v[82:83], v[82:83], v[240:241] op_sel:[0,1] op_sel_hi:[1,1]
	v_pk_mul_f32 v[96:97], v[96:97], v[240:241] op_sel:[0,1] op_sel_hi:[1,1]
	v_pk_mul_f32 v[98:99], v[98:99], v[240:241] op_sel:[0,1] op_sel_hi:[1,1]
	v_pk_mul_f32 v[64:65], v[64:65], v[240:241] op_sel:[0,1] op_sel_hi:[1,1]
	v_pk_mul_f32 v[66:67], v[66:67], v[240:241] op_sel:[0,1] op_sel_hi:[1,1]
	v_pk_mul_f32 v[60:61], v[60:61], v[242:243] op_sel_hi:[1,0]
	v_pk_mul_f32 v[62:63], v[62:63], v[242:243] op_sel_hi:[1,0]
	v_pk_mul_f32 v[28:29], v[28:29], v[242:243] op_sel_hi:[1,0]
	v_pk_mul_f32 v[30:31], v[30:31], v[242:243] op_sel_hi:[1,0]
	v_pk_mul_f32 v[44:45], v[44:45], v[242:243] op_sel_hi:[1,0]
	v_pk_mul_f32 v[46:47], v[46:47], v[242:243] op_sel_hi:[1,0]
	v_pk_mul_f32 v[12:13], v[12:13], v[242:243] op_sel_hi:[1,0]
	v_pk_mul_f32 v[14:15], v[14:15], v[242:243] op_sel_hi:[1,0]
	v_pk_mul_f32 v[52:53], v[52:53], v[242:243] op_sel:[0,1] op_sel_hi:[1,1]
	v_pk_mul_f32 v[54:55], v[54:55], v[242:243] op_sel:[0,1] op_sel_hi:[1,1]
	v_pk_mul_f32 v[20:21], v[20:21], v[242:243] op_sel:[0,1] op_sel_hi:[1,1]
	v_pk_mul_f32 v[22:23], v[22:23], v[242:243] op_sel:[0,1] op_sel_hi:[1,1]
	v_pk_mul_f32 v[36:37], v[36:37], v[242:243] op_sel:[0,1] op_sel_hi:[1,1]
	v_pk_mul_f32 v[38:39], v[38:39], v[242:243] op_sel:[0,1] op_sel_hi:[1,1]
	v_pk_mul_f32 v[4:5], v[4:5], v[242:243] op_sel:[0,1] op_sel_hi:[1,1]
	v_pk_mul_f32 v[6:7], v[6:7], v[242:243] op_sel:[0,1] op_sel_hi:[1,1]
	v_pk_mul_f32 v[48:49], v[48:49], v[244:245] op_sel_hi:[1,0]
	v_pk_mul_f32 v[50:51], v[50:51], v[244:245] op_sel_hi:[1,0]
	v_pk_mul_f32 v[16:17], v[16:17], v[244:245] op_sel_hi:[1,0]
	v_pk_mul_f32 v[18:19], v[18:19], v[244:245] op_sel_hi:[1,0]
	v_pk_mul_f32 v[32:33], v[32:33], v[244:245] op_sel_hi:[1,0]
	v_pk_mul_f32 v[34:35], v[34:35], v[244:245] op_sel_hi:[1,0]
	v_pk_mul_f32 v[0:1], v[0:1], v[244:245] op_sel_hi:[1,0]
	v_pk_mul_f32 v[2:3], v[2:3], v[244:245] op_sel_hi:[1,0]
	v_pk_mul_f32 v[56:57], v[56:57], v[244:245] op_sel:[0,1] op_sel_hi:[1,1]
	v_pk_mul_f32 v[58:59], v[58:59], v[244:245] op_sel:[0,1] op_sel_hi:[1,1]
	v_pk_mul_f32 v[24:25], v[24:25], v[244:245] op_sel:[0,1] op_sel_hi:[1,1]
	v_pk_mul_f32 v[26:27], v[26:27], v[244:245] op_sel:[0,1] op_sel_hi:[1,1]
	v_pk_mul_f32 v[40:41], v[40:41], v[244:245] op_sel:[0,1] op_sel_hi:[1,1]
	v_pk_mul_f32 v[42:43], v[42:43], v[244:245] op_sel:[0,1] op_sel_hi:[1,1]
	v_pk_mul_f32 v[8:9], v[8:9], v[244:245] op_sel:[0,1] op_sel_hi:[1,1]
	v_pk_mul_f32 v[10:11], v[10:11], v[244:245] op_sel:[0,1] op_sel_hi:[1,1]
	s_waitcnt lgkmcnt(0)
; __device__ __forceinline__ f32x2 gelu_pk(f32x2 v) {
;     const f32x2 av = __builtin_elementwise_abs(v), d = av * 0.2316418882f + 1.0f;
;     f32x2 t; t.x = __builtin_amdgcn_rcpf(d.x); t.y = __builtin_amdgcn_rcpf(d.y);
;     __device__ __forceinline__ void operator()(const f32x4 (&acc)[2][2][4][2], const Unit& u, int wr, int wc, int fr, int fq) const {
;     ...
;                     for (int m = 0; m < 4; ++m) {
;                         f32x4 cv;
;                         if (!samp) {
;                             const f32x4 prev = m ? v[m - 1] : hv;
; #pragma unroll
;                             for (int e = 0; e < 4; ++e) {
;                                 const int vi = __float_as_int(v[m][e]), pi = __float_as_int(prev[e]);
;                                 const int o1 = __builtin_amdgcn_mov_dpp(pi, 0x121, 0xf, 0xf, false);
;                                 const int o2 = __builtin_amdgcn_mov_dpp(pi, 0x122, 0xf, 0xf, false);
;                                 const float p1 = __int_as_float(__builtin_amdgcn_update_dpp(o1, vi, 0x111, 0xf, 0xf, false));
;                                 const float p2 = __int_as_float(__builtin_amdgcn_update_dpp(o2, vi, 0x112, 0xf, 0xf, false));
;                                 cv[e] = cb[e] + cw0[e] * p2 + cw1[e] * p1 + cw2[e] * v[m][e];
;                             }
;                         } else {
;                             const int ns = rowb + 16 * m + fr - MP;
;                             f32x4 s0 = (f32x4){0.f, 0.f, 0.f, 0.f}, s1 = s0;
;                             if (ns < NS) {
;                                 s0 = *(const f32x4*)(state + (size_t)(ns * 2 + 0) * FF2 + oc); s1 = *(const f32x4*)(state + (size_t)(ns * 2 + 1) * FF2 + oc);
;                                 *(f32x4*)(ncs + (size_t)(ns * 2 + 0) * FF2 + oc) = s1; *(f32x4*)(ncs + (size_t)(ns * 2 + 1) * FF2 + oc) = v[m];
;                             }
;                             cv = cb + cw0 * s0 + cw1 * s1 + cw2 * v[m];
;                         }
;                         if (bj == 0) cg[m] = gelu4(cv);
;                         else {
;                             const f32x4 r = cg[m] * cv;
;                             v2u w; w.x = cvt_pk_bf16(r[0], r[1]); w.y = cvt_pk_bf16(r[2], r[3]);
;                             *(v2u*)(ACT + (size_t)(rowb + 16 * m + fr) * FF + 128 * u.pn + 32 * wc + 8 * fq + 4 * n) = w;
;                         }
	v_mbcnt_lo_u32_b32 v218, -1, 0
	v_mbcnt_hi_u32_b32 v218, -1, v218
	v_and_b32_e32 v218, 12, v218
	v_cmp_eq_u32_e32 vcc, 12, v218
	s_nop 1
	v_cndmask_b32_e64 v218, 0, 1.0, vcc
	s_mov_b32 s56, 0x3f07dc22
	v_pk_mul_f32 v[220:221], v[116:117], v[218:219] op_sel_hi:[1,0]
	v_pk_mul_f32 v[222:223], v[118:119], v[218:219] op_sel_hi:[1,0]
	v_pk_fma_f32 v[254:255], v[202:203], v[112:113], v[132:133]
	v_pk_fma_f32 v[148:149], v[204:205], v[114:115], v[134:135]
	v_fmac_f32_dpp v254, v112, v186 row_shr:1 row_mask:0xf bank_mask:0xf
	v_fmac_f32_dpp v255, v113, v187 row_shr:1 row_mask:0xf bank_mask:0xf
	v_fmac_f32_dpp v148, v114, v188 row_shr:1 row_mask:0xf bank_mask:0xf
	v_fmac_f32_dpp v149, v115, v189 row_shr:1 row_mask:0xf bank_mask:0xf
	v_fmac_f32_dpp v254, v112, v170 row_shr:2 row_mask:0xf bank_mask:0xf
	v_fmac_f32_dpp v255, v113, v171 row_shr:2 row_mask:0xf bank_mask:0xf
	v_fmac_f32_dpp v148, v114, v172 row_shr:2 row_mask:0xf bank_mask:0xf
	v_fmac_f32_dpp v149, v115, v173 row_shr:2 row_mask:0xf bank_mask:0xf
	v_fmac_f32_dpp v254, v220, v186 row_ror:1 row_mask:0xf bank_mask:0x1
	v_fmac_f32_dpp v255, v221, v187 row_ror:1 row_mask:0xf bank_mask:0x1
	v_fmac_f32_dpp v148, v222, v188 row_ror:1 row_mask:0xf bank_mask:0x1
	v_fmac_f32_dpp v149, v223, v189 row_ror:1 row_mask:0xf bank_mask:0x1
	v_fmac_f32_dpp v254, v220, v170 row_ror:2 row_mask:0xf bank_mask:0x1
	v_fmac_f32_dpp v255, v221, v171 row_ror:2 row_mask:0xf bank_mask:0x1
	v_fmac_f32_dpp v148, v222, v172 row_ror:2 row_mask:0xf bank_mask:0x1
	v_fmac_f32_dpp v149, v223, v173 row_ror:2 row_mask:0xf bank_mask:0x1
	v_fma_f32 v246, |v254|, s38, 1.0
	v_fma_f32 v247, |v255|, s38, 1.0
	v_fma_f32 v248, |v148|, s38, 1.0
	v_fma_f32 v249, |v149|, s38, 1.0
	v_pk_mul_f32 v[250:251], v[254:255], v[254:255]
	v_pk_mul_f32 v[252:253], v[148:149], v[148:149]
	v_rcp_f32_e32 v246, v246
	v_rcp_f32_e32 v247, v247
	v_rcp_f32_e32 v248, v248
	v_rcp_f32_e32 v249, v249
	v_pk_mul_f32 v[250:251], v[250:251], s[72:73] op_sel_hi:[1,0]
	v_pk_mul_f32 v[252:253], v[252:253], s[72:73] op_sel_hi:[1,0]
	v_exp_f32_e32 v250, v250
	v_exp_f32_e32 v251, v251
	v_exp_f32_e32 v252, v252
	v_exp_f32_e32 v253, v253
	v_pk_fma_f32 v[238:239], v[246:247], s[56:57], v[218:219] op_sel:[0,0,1] op_sel_hi:[1,0,1]
	v_pk_fma_f32 v[240:241], v[248:249], s[56:57], v[218:219] op_sel:[0,0,1] op_sel_hi:[1,0,1]
	v_pk_fma_f32 v[238:239], v[246:247], v[238:239], s[66:67] op_sel_hi:[1,1,0]
	v_pk_fma_f32 v[240:241], v[248:249], v[240:241], s[66:67] op_sel_hi:[1,1,0]
	v_pk_fma_f32 v[238:239], v[246:247], v[238:239], s[68:69] op_sel_hi:[1,1,0]
	v_pk_fma_f32 v[240:241], v[248:249], v[240:241], s[68:69] op_sel_hi:[1,1,0]
	v_pk_fma_f32 v[238:239], v[246:247], v[238:239], s[70:71] op_sel_hi:[1,1,0]
	v_pk_fma_f32 v[240:241], v[248:249], v[240:241], s[70:71] op_sel_hi:[1,1,0]
	v_pk_mul_f32 v[238:239], v[246:247], v[238:239]
	v_pk_mul_f32 v[240:241], v[248:249], v[240:241]
	v_pk_mul_f32 v[238:239], v[250:251], v[238:239]
	v_pk_mul_f32 v[240:241], v[252:253], v[240:241]
	v_max_f32_e32 v246, 0, v254
	v_max_f32_e32 v247, 0, v255
	v_max_f32_e32 v248, 0, v148
	v_max_f32_e32 v249, 0, v149
	v_fma_f32 v238, -|v254|, v238, v246
	v_fma_f32 v239, -|v255|, v239, v247
	v_fma_f32 v240, -|v148|, v240, v248
	v_fma_f32 v241, -|v149|, v241, v249
	v_pk_mul_f32 v[220:221], v[100:101], v[218:219] op_sel_hi:[1,0]
	v_pk_mul_f32 v[222:223], v[102:103], v[218:219] op_sel_hi:[1,0]
	v_pk_fma_f32 v[254:255], v[210:211], v[96:97], v[140:141]
	v_pk_fma_f32 v[148:149], v[212:213], v[98:99], v[142:143]
	v_fmac_f32_dpp v254, v96, v194 row_shr:1 row_mask:0xf bank_mask:0xf
	v_fmac_f32_dpp v255, v97, v195 row_shr:1 row_mask:0xf bank_mask:0xf
	v_fmac_f32_dpp v148, v98, v196 row_shr:1 row_mask:0xf bank_mask:0xf
	v_fmac_f32_dpp v149, v99, v197 row_shr:1 row_mask:0xf bank_mask:0xf
	v_fmac_f32_dpp v254, v96, v178 row_shr:2 row_mask:0xf bank_mask:0xf
	v_fmac_f32_dpp v255, v97, v179 row_shr:2 row_mask:0xf bank_mask:0xf
	v_fmac_f32_dpp v148, v98, v180 row_shr:2 row_mask:0xf bank_mask:0xf
	v_fmac_f32_dpp v149, v99, v181 row_shr:2 row_mask:0xf bank_mask:0xf
	v_fmac_f32_dpp v254, v220, v194 row_ror:1 row_mask:0xf bank_mask:0x1
	v_fmac_f32_dpp v255, v221, v195 row_ror:1 row_mask:0xf bank_mask:0x1
	v_fmac_f32_dpp v148, v222, v196 row_ror:1 row_mask:0xf bank_mask:0x1
	v_fmac_f32_dpp v149, v223, v197 row_ror:1 row_mask:0xf bank_mask:0x1
	v_fmac_f32_dpp v254, v220, v178 row_ror:2 row_mask:0xf bank_mask:0x1
	v_fmac_f32_dpp v255, v221, v179 row_ror:2 row_mask:0xf bank_mask:0x1
	v_fmac_f32_dpp v148, v222, v180 row_ror:2 row_mask:0xf bank_mask:0x1
	v_fmac_f32_dpp v149, v223, v181 row_ror:2 row_mask:0xf bank_mask:0x1
	v_pk_mul_f32 v[254:255], v[238:239], v[254:255]
	v_pk_mul_f32 v[148:149], v[240:241], v[148:149]
	v_cvt_pk_bf16_f32 v242, v254, v255
	v_cvt_pk_bf16_f32 v243, v148, v149
	v_pk_mul_f32 v[220:221], v[84:85], v[218:219] op_sel_hi:[1,0]
	v_pk_mul_f32 v[222:223], v[86:87], v[218:219] op_sel_hi:[1,0]
	v_pk_fma_f32 v[254:255], v[206:207], v[80:81], v[136:137]
	v_pk_fma_f32 v[148:149], v[208:209], v[82:83], v[138:139]
	v_fmac_f32_dpp v254, v80, v190 row_shr:1 row_mask:0xf bank_mask:0xf
	v_fmac_f32_dpp v255, v81, v191 row_shr:1 row_mask:0xf bank_mask:0xf
	v_fmac_f32_dpp v148, v82, v192 row_shr:1 row_mask:0xf bank_mask:0xf
	v_fmac_f32_dpp v149, v83, v193 row_shr:1 row_mask:0xf bank_mask:0xf
	v_fmac_f32_dpp v254, v80, v174 row_shr:2 row_mask:0xf bank_mask:0xf
	v_fmac_f32_dpp v255, v81, v175 row_shr:2 row_mask:0xf bank_mask:0xf
	v_fmac_f32_dpp v148, v82, v176 row_shr:2 row_mask:0xf bank_mask:0xf
	v_fmac_f32_dpp v149, v83, v177 row_shr:2 row_mask:0xf bank_mask:0xf
	v_fmac_f32_dpp v254, v220, v190 row_ror:1 row_mask:0xf bank_mask:0x1
; __device__ __forceinline__ f32x2 gelu_pk(f32x2 v) {
;     const f32x2 av = __builtin_elementwise_abs(v), d = av * 0.2316418882f + 1.0f;
;     f32x2 t; t.x = __builtin_amdgcn_rcpf(d.x); t.y = __builtin_amdgcn_rcpf(d.y);
;     __device__ __forceinline__ void operator()(const f32x4 (&acc)[2][2][4][2], const Unit& u, int wr, int wc, int fr, int fq) const {
;     ...
;                     for (int m = 0; m < 4; ++m) {
;                         f32x4 cv;
;                         if (!samp) {
;                             const f32x4 prev = m ? v[m - 1] : hv;
; #pragma unroll
;                             for (int e = 0; e < 4; ++e) {
;                                 const int vi = __float_as_int(v[m][e]), pi = __float_as_int(prev[e]);
;                                 const int o1 = __builtin_amdgcn_mov_dpp(pi, 0x121, 0xf, 0xf, false);
;                                 const int o2 = __builtin_amdgcn_mov_dpp(pi, 0x122, 0xf, 0xf, false);
;                                 const float p1 = __int_as_float(__builtin_amdgcn_update_dpp(o1, vi, 0x111, 0xf, 0xf, false));
;                                 const float p2 = __int_as_float(__builtin_amdgcn_update_dpp(o2, vi, 0x112, 0xf, 0xf, false));
;                                 cv[e] = cb[e] + cw0[e] * p2 + cw1[e] * p1 + cw2[e] * v[m][e];
;                             }
;                         } else {
;                             const int ns = rowb + 16 * m + fr - MP;
;                             f32x4 s0 = (f32x4){0.f, 0.f, 0.f, 0.f}, s1 = s0;
;                             if (ns < NS) {
;                                 s0 = *(const f32x4*)(state + (size_t)(ns * 2 + 0) * FF2 + oc); s1 = *(const f32x4*)(state + (size_t)(ns * 2 + 1) * FF2 + oc);
;                                 *(f32x4*)(ncs + (size_t)(ns * 2 + 0) * FF2 + oc) = s1; *(f32x4*)(ncs + (size_t)(ns * 2 + 1) * FF2 + oc) = v[m];
;                             }
;                             cv = cb + cw0 * s0 + cw1 * s1 + cw2 * v[m];
;                         }
;                         if (bj == 0) cg[m] = gelu4(cv);
;                         else {
;                             const f32x4 r = cg[m] * cv;
;                             v2u w; w.x = cvt_pk_bf16(r[0], r[1]); w.y = cvt_pk_bf16(r[2], r[3]);
;                             *(v2u*)(ACT + (size_t)(rowb + 16 * m + fr) * FF + 128 * u.pn + 32 * wc + 8 * fq + 4 * n) = w;
;                         }
	v_fmac_f32_dpp v255, v221, v191 row_ror:1 row_mask:0xf bank_mask:0x1
	v_fmac_f32_dpp v148, v222, v192 row_ror:1 row_mask:0xf bank_mask:0x1
	v_fmac_f32_dpp v149, v223, v193 row_ror:1 row_mask:0xf bank_mask:0x1
	v_fmac_f32_dpp v254, v220, v174 row_ror:2 row_mask:0xf bank_mask:0x1
	v_fmac_f32_dpp v255, v221, v175 row_ror:2 row_mask:0xf bank_mask:0x1
	v_fmac_f32_dpp v148, v222, v176 row_ror:2 row_mask:0xf bank_mask:0x1
	v_fmac_f32_dpp v149, v223, v177 row_ror:2 row_mask:0xf bank_mask:0x1
	v_fma_f32 v246, |v254|, s38, 1.0
	v_fma_f32 v247, |v255|, s38, 1.0
	v_fma_f32 v248, |v148|, s38, 1.0
	v_fma_f32 v249, |v149|, s38, 1.0
	v_pk_mul_f32 v[250:251], v[254:255], v[254:255]
	v_pk_mul_f32 v[252:253], v[148:149], v[148:149]
	v_rcp_f32_e32 v246, v246
	v_rcp_f32_e32 v247, v247
	v_rcp_f32_e32 v248, v248
	v_rcp_f32_e32 v249, v249
	v_pk_mul_f32 v[250:251], v[250:251], s[72:73] op_sel_hi:[1,0]
	v_pk_mul_f32 v[252:253], v[252:253], s[72:73] op_sel_hi:[1,0]
	v_exp_f32_e32 v250, v250
	v_exp_f32_e32 v251, v251
	v_exp_f32_e32 v252, v252
	v_exp_f32_e32 v253, v253
	v_pk_fma_f32 v[238:239], v[246:247], s[56:57], v[218:219] op_sel:[0,0,1] op_sel_hi:[1,0,1]
	v_pk_fma_f32 v[240:241], v[248:249], s[56:57], v[218:219] op_sel:[0,0,1] op_sel_hi:[1,0,1]
	v_pk_fma_f32 v[238:239], v[246:247], v[238:239], s[66:67] op_sel_hi:[1,1,0]
	v_pk_fma_f32 v[240:241], v[248:249], v[240:241], s[66:67] op_sel_hi:[1,1,0]
	v_pk_fma_f32 v[238:239], v[246:247], v[238:239], s[68:69] op_sel_hi:[1,1,0]
	v_pk_fma_f32 v[240:241], v[248:249], v[240:241], s[68:69] op_sel_hi:[1,1,0]
	v_pk_fma_f32 v[238:239], v[246:247], v[238:239], s[70:71] op_sel_hi:[1,1,0]
	v_pk_fma_f32 v[240:241], v[248:249], v[240:241], s[70:71] op_sel_hi:[1,1,0]
	v_pk_mul_f32 v[238:239], v[246:247], v[238:239]
	v_pk_mul_f32 v[240:241], v[248:249], v[240:241]
	v_pk_mul_f32 v[238:239], v[250:251], v[238:239]
	v_pk_mul_f32 v[240:241], v[252:253], v[240:241]
	v_max_f32_e32 v246, 0, v254
	v_max_f32_e32 v247, 0, v255
	v_max_f32_e32 v248, 0, v148
	v_max_f32_e32 v249, 0, v149
	v_fma_f32 v238, -|v254|, v238, v246
	v_fma_f32 v239, -|v255|, v239, v247
	v_fma_f32 v240, -|v148|, v240, v248
	v_fma_f32 v241, -|v149|, v241, v249
	v_pk_mul_f32 v[220:221], v[68:69], v[218:219] op_sel_hi:[1,0]
	v_pk_mul_f32 v[222:223], v[70:71], v[218:219] op_sel_hi:[1,0]
	v_pk_fma_f32 v[254:255], v[128:129], v[64:65], v[144:145]
	v_pk_fma_f32 v[148:149], v[130:131], v[66:67], v[146:147]
	v_fmac_f32_dpp v254, v64, v198 row_shr:1 row_mask:0xf bank_mask:0xf
	v_fmac_f32_dpp v255, v65, v199 row_shr:1 row_mask:0xf bank_mask:0xf
	v_fmac_f32_dpp v148, v66, v200 row_shr:1 row_mask:0xf bank_mask:0xf
	v_fmac_f32_dpp v149, v67, v201 row_shr:1 row_mask:0xf bank_mask:0xf
	v_fmac_f32_dpp v254, v64, v182 row_shr:2 row_mask:0xf bank_mask:0xf
	v_fmac_f32_dpp v255, v65, v183 row_shr:2 row_mask:0xf bank_mask:0xf
	v_fmac_f32_dpp v148, v66, v184 row_shr:2 row_mask:0xf bank_mask:0xf
	v_fmac_f32_dpp v149, v67, v185 row_shr:2 row_mask:0xf bank_mask:0xf
	v_fmac_f32_dpp v254, v220, v198 row_ror:1 row_mask:0xf bank_mask:0x1
	v_fmac_f32_dpp v255, v221, v199 row_ror:1 row_mask:0xf bank_mask:0x1
	v_fmac_f32_dpp v148, v222, v200 row_ror:1 row_mask:0xf bank_mask:0x1
	v_fmac_f32_dpp v149, v223, v201 row_ror:1 row_mask:0xf bank_mask:0x1
	v_fmac_f32_dpp v254, v220, v182 row_ror:2 row_mask:0xf bank_mask:0x1
	v_fmac_f32_dpp v255, v221, v183 row_ror:2 row_mask:0xf bank_mask:0x1
	v_fmac_f32_dpp v148, v222, v184 row_ror:2 row_mask:0xf bank_mask:0x1
	v_fmac_f32_dpp v149, v223, v185 row_ror:2 row_mask:0xf bank_mask:0x1
	v_pk_mul_f32 v[254:255], v[238:239], v[254:255]
	v_pk_mul_f32 v[148:149], v[240:241], v[148:149]
	v_cvt_pk_bf16_f32 v244, v254, v255
	v_cvt_pk_bf16_f32 v245, v148, v149
	s_add_u32 s56, s46, 0x42000
	s_addc_u32 s57, s47, 0
	global_store_dwordx4 v151, v[242:245], s[56:57]
	v_mov_b32_e32 v112, 0
	v_mov_b32_e32 v113, 0
	v_mov_b32_e32 v114, 0
	v_mov_b32_e32 v115, 0
	s_mov_b32 s56, 0x3f07dc22
	v_pk_mul_f32 v[112:113], v[120:121], v[218:219] op_sel_hi:[1,0]
	v_pk_mul_f32 v[114:115], v[122:123], v[218:219] op_sel_hi:[1,0]
	v_pk_fma_f32 v[254:255], v[202:203], v[116:117], v[132:133]
	v_pk_fma_f32 v[148:149], v[204:205], v[118:119], v[134:135]
	v_fmac_f32_dpp v254, v116, v186 row_shr:1 row_mask:0xf bank_mask:0xf
	v_fmac_f32_dpp v255, v117, v187 row_shr:1 row_mask:0xf bank_mask:0xf
	v_fmac_f32_dpp v148, v118, v188 row_shr:1 row_mask:0xf bank_mask:0xf
	v_fmac_f32_dpp v149, v119, v189 row_shr:1 row_mask:0xf bank_mask:0xf
	v_fmac_f32_dpp v254, v116, v170 row_shr:2 row_mask:0xf bank_mask:0xf
	v_fmac_f32_dpp v255, v117, v171 row_shr:2 row_mask:0xf bank_mask:0xf
	v_fmac_f32_dpp v148, v118, v172 row_shr:2 row_mask:0xf bank_mask:0xf
	v_fmac_f32_dpp v149, v119, v173 row_shr:2 row_mask:0xf bank_mask:0xf
	v_fmac_f32_dpp v254, v112, v186 row_ror:1 row_mask:0xf bank_mask:0x1
	v_fmac_f32_dpp v255, v113, v187 row_ror:1 row_mask:0xf bank_mask:0x1
	v_fmac_f32_dpp v148, v114, v188 row_ror:1 row_mask:0xf bank_mask:0x1
	v_fmac_f32_dpp v149, v115, v189 row_ror:1 row_mask:0xf bank_mask:0x1
	v_fmac_f32_dpp v254, v112, v170 row_ror:2 row_mask:0xf bank_mask:0x1
	v_fmac_f32_dpp v255, v113, v171 row_ror:2 row_mask:0xf bank_mask:0x1
	v_fmac_f32_dpp v148, v114, v172 row_ror:2 row_mask:0xf bank_mask:0x1
	v_fmac_f32_dpp v149, v115, v173 row_ror:2 row_mask:0xf bank_mask:0x1
	v_fma_f32 v246, |v254|, s38, 1.0
	v_fma_f32 v247, |v255|, s38, 1.0
	v_fma_f32 v248, |v148|, s38, 1.0
	v_fma_f32 v249, |v149|, s38, 1.0
	v_pk_mul_f32 v[250:251], v[254:255], v[254:255]
	v_pk_mul_f32 v[252:253], v[148:149], v[148:149]
	v_rcp_f32_e32 v246, v246
	v_rcp_f32_e32 v247, v247
	v_rcp_f32_e32 v248, v248
	v_rcp_f32_e32 v249, v249
; __device__ __forceinline__ f32x2 gelu_pk(f32x2 v) {
;     const f32x2 av = __builtin_elementwise_abs(v), d = av * 0.2316418882f + 1.0f;
;     f32x2 t; t.x = __builtin_amdgcn_rcpf(d.x); t.y = __builtin_amdgcn_rcpf(d.y);
;     __device__ __forceinline__ void operator()(const f32x4 (&acc)[2][2][4][2], const Unit& u, int wr, int wc, int fr, int fq) const {
;     ...
;                     for (int m = 0; m < 4; ++m) {
;                         f32x4 cv;
;                         if (!samp) {
;                             const f32x4 prev = m ? v[m - 1] : hv;
; #pragma unroll
;                             for (int e = 0; e < 4; ++e) {
;                                 const int vi = __float_as_int(v[m][e]), pi = __float_as_int(prev[e]);
;                                 const int o1 = __builtin_amdgcn_mov_dpp(pi, 0x121, 0xf, 0xf, false);
;                                 const int o2 = __builtin_amdgcn_mov_dpp(pi, 0x122, 0xf, 0xf, false);
;                                 const float p1 = __int_as_float(__builtin_amdgcn_update_dpp(o1, vi, 0x111, 0xf, 0xf, false));
;                                 const float p2 = __int_as_float(__builtin_amdgcn_update_dpp(o2, vi, 0x112, 0xf, 0xf, false));
;                                 cv[e] = cb[e] + cw0[e] * p2 + cw1[e] * p1 + cw2[e] * v[m][e];
;                             }
;                         } else {
;                             const int ns = rowb + 16 * m + fr - MP;
;                             f32x4 s0 = (f32x4){0.f, 0.f, 0.f, 0.f}, s1 = s0;
;                             if (ns < NS) {
;                                 s0 = *(const f32x4*)(state + (size_t)(ns * 2 + 0) * FF2 + oc); s1 = *(const f32x4*)(state + (size_t)(ns * 2 + 1) * FF2 + oc);
;                                 *(f32x4*)(ncs + (size_t)(ns * 2 + 0) * FF2 + oc) = s1; *(f32x4*)(ncs + (size_t)(ns * 2 + 1) * FF2 + oc) = v[m];
;                             }
;                             cv = cb + cw0 * s0 + cw1 * s1 + cw2 * v[m];
;                         }
;                         if (bj == 0) cg[m] = gelu4(cv);
;                         else {
;                             const f32x4 r = cg[m] * cv;
;                             v2u w; w.x = cvt_pk_bf16(r[0], r[1]); w.y = cvt_pk_bf16(r[2], r[3]);
;                             *(v2u*)(ACT + (size_t)(rowb + 16 * m + fr) * FF + 128 * u.pn + 32 * wc + 8 * fq + 4 * n) = w;
;                         }
	v_pk_mul_f32 v[250:251], v[250:251], s[72:73] op_sel_hi:[1,0]
	v_pk_mul_f32 v[252:253], v[252:253], s[72:73] op_sel_hi:[1,0]
	v_exp_f32_e32 v250, v250
	v_exp_f32_e32 v251, v251
	v_exp_f32_e32 v252, v252
	v_exp_f32_e32 v253, v253
	v_pk_fma_f32 v[238:239], v[246:247], s[56:57], v[218:219] op_sel:[0,0,1] op_sel_hi:[1,0,1]
	v_pk_fma_f32 v[240:241], v[248:249], s[56:57], v[218:219] op_sel:[0,0,1] op_sel_hi:[1,0,1]
	v_pk_fma_f32 v[238:239], v[246:247], v[238:239], s[66:67] op_sel_hi:[1,1,0]
	v_pk_fma_f32 v[240:241], v[248:249], v[240:241], s[66:67] op_sel_hi:[1,1,0]
	v_pk_fma_f32 v[238:239], v[246:247], v[238:239], s[68:69] op_sel_hi:[1,1,0]
	v_pk_fma_f32 v[240:241], v[248:249], v[240:241], s[68:69] op_sel_hi:[1,1,0]
	v_pk_fma_f32 v[238:239], v[246:247], v[238:239], s[70:71] op_sel_hi:[1,1,0]
	v_pk_fma_f32 v[240:241], v[248:249], v[240:241], s[70:71] op_sel_hi:[1,1,0]
	v_pk_mul_f32 v[238:239], v[246:247], v[238:239]
	v_pk_mul_f32 v[240:241], v[248:249], v[240:241]
	v_pk_mul_f32 v[238:239], v[250:251], v[238:239]
	v_pk_mul_f32 v[240:241], v[252:253], v[240:241]
	v_max_f32_e32 v246, 0, v254
	v_max_f32_e32 v247, 0, v255
	v_max_f32_e32 v248, 0, v148
	v_max_f32_e32 v249, 0, v149
	v_fma_f32 v238, -|v254|, v238, v246
	v_fma_f32 v239, -|v255|, v239, v247
	v_fma_f32 v240, -|v148|, v240, v248
	v_fma_f32 v241, -|v149|, v241, v249
	v_pk_mul_f32 v[112:113], v[104:105], v[218:219] op_sel_hi:[1,0]
	v_pk_mul_f32 v[114:115], v[106:107], v[218:219] op_sel_hi:[1,0]
	v_pk_fma_f32 v[254:255], v[210:211], v[100:101], v[140:141]
	v_pk_fma_f32 v[148:149], v[212:213], v[102:103], v[142:143]
	v_fmac_f32_dpp v254, v100, v194 row_shr:1 row_mask:0xf bank_mask:0xf
	v_fmac_f32_dpp v255, v101, v195 row_shr:1 row_mask:0xf bank_mask:0xf
	v_fmac_f32_dpp v148, v102, v196 row_shr:1 row_mask:0xf bank_mask:0xf
	v_fmac_f32_dpp v149, v103, v197 row_shr:1 row_mask:0xf bank_mask:0xf
	v_fmac_f32_dpp v254, v100, v178 row_shr:2 row_mask:0xf bank_mask:0xf
	v_fmac_f32_dpp v255, v101, v179 row_shr:2 row_mask:0xf bank_mask:0xf
	v_fmac_f32_dpp v148, v102, v180 row_shr:2 row_mask:0xf bank_mask:0xf
	v_fmac_f32_dpp v149, v103, v181 row_shr:2 row_mask:0xf bank_mask:0xf
	v_fmac_f32_dpp v254, v112, v194 row_ror:1 row_mask:0xf bank_mask:0x1
	v_fmac_f32_dpp v255, v113, v195 row_ror:1 row_mask:0xf bank_mask:0x1
	v_fmac_f32_dpp v148, v114, v196 row_ror:1 row_mask:0xf bank_mask:0x1
	v_fmac_f32_dpp v149, v115, v197 row_ror:1 row_mask:0xf bank_mask:0x1
	v_fmac_f32_dpp v254, v112, v178 row_ror:2 row_mask:0xf bank_mask:0x1
	v_fmac_f32_dpp v255, v113, v179 row_ror:2 row_mask:0xf bank_mask:0x1
	v_fmac_f32_dpp v148, v114, v180 row_ror:2 row_mask:0xf bank_mask:0x1
	v_fmac_f32_dpp v149, v115, v181 row_ror:2 row_mask:0xf bank_mask:0x1
	v_pk_mul_f32 v[254:255], v[238:239], v[254:255]
	v_pk_mul_f32 v[148:149], v[240:241], v[148:149]
	v_cvt_pk_bf16_f32 v242, v254, v255
	v_cvt_pk_bf16_f32 v243, v148, v149
	v_pk_mul_f32 v[112:113], v[88:89], v[218:219] op_sel_hi:[1,0]
	v_pk_mul_f32 v[114:115], v[90:91], v[218:219] op_sel_hi:[1,0]
	v_pk_fma_f32 v[254:255], v[206:207], v[84:85], v[136:137]
	v_pk_fma_f32 v[148:149], v[208:209], v[86:87], v[138:139]
	v_fmac_f32_dpp v254, v84, v190 row_shr:1 row_mask:0xf bank_mask:0xf
	v_fmac_f32_dpp v255, v85, v191 row_shr:1 row_mask:0xf bank_mask:0xf
	v_fmac_f32_dpp v148, v86, v192 row_shr:1 row_mask:0xf bank_mask:0xf
	v_fmac_f32_dpp v149, v87, v193 row_shr:1 row_mask:0xf bank_mask:0xf
	v_fmac_f32_dpp v254, v84, v174 row_shr:2 row_mask:0xf bank_mask:0xf
	v_fmac_f32_dpp v255, v85, v175 row_shr:2 row_mask:0xf bank_mask:0xf
	v_fmac_f32_dpp v148, v86, v176 row_shr:2 row_mask:0xf bank_mask:0xf
	v_fmac_f32_dpp v149, v87, v177 row_shr:2 row_mask:0xf bank_mask:0xf
	v_fmac_f32_dpp v254, v112, v190 row_ror:1 row_mask:0xf bank_mask:0x1
	v_fmac_f32_dpp v255, v113, v191 row_ror:1 row_mask:0xf bank_mask:0x1
	v_fmac_f32_dpp v148, v114, v192 row_ror:1 row_mask:0xf bank_mask:0x1
	v_fmac_f32_dpp v149, v115, v193 row_ror:1 row_mask:0xf bank_mask:0x1
	v_fmac_f32_dpp v254, v112, v174 row_ror:2 row_mask:0xf bank_mask:0x1
	v_fmac_f32_dpp v255, v113, v175 row_ror:2 row_mask:0xf bank_mask:0x1
	v_fmac_f32_dpp v148, v114, v176 row_ror:2 row_mask:0xf bank_mask:0x1
	v_fmac_f32_dpp v149, v115, v177 row_ror:2 row_mask:0xf bank_mask:0x1
	v_fma_f32 v246, |v254|, s38, 1.0
	v_fma_f32 v247, |v255|, s38, 1.0
	v_fma_f32 v248, |v148|, s38, 1.0
	v_fma_f32 v249, |v149|, s38, 1.0
	v_pk_mul_f32 v[250:251], v[254:255], v[254:255]
	v_pk_mul_f32 v[252:253], v[148:149], v[148:149]
	v_rcp_f32_e32 v246, v246
	v_rcp_f32_e32 v247, v247
	v_rcp_f32_e32 v248, v248
	v_rcp_f32_e32 v249, v249
	v_pk_mul_f32 v[250:251], v[250:251], s[72:73] op_sel_hi:[1,0]
	v_pk_mul_f32 v[252:253], v[252:253], s[72:73] op_sel_hi:[1,0]
	v_exp_f32_e32 v250, v250
	v_exp_f32_e32 v251, v251
	v_exp_f32_e32 v252, v252
	v_exp_f32_e32 v253, v253
	v_pk_fma_f32 v[238:239], v[246:247], s[56:57], v[218:219] op_sel:[0,0,1] op_sel_hi:[1,0,1]
	v_pk_fma_f32 v[240:241], v[248:249], s[56:57], v[218:219] op_sel:[0,0,1] op_sel_hi:[1,0,1]
	v_pk_fma_f32 v[238:239], v[246:247], v[238:239], s[66:67] op_sel_hi:[1,1,0]
	v_pk_fma_f32 v[240:241], v[248:249], v[240:241], s[66:67] op_sel_hi:[1,1,0]
	v_pk_fma_f32 v[238:239], v[246:247], v[238:239], s[68:69] op_sel_hi:[1,1,0]
	v_pk_fma_f32 v[240:241], v[248:249], v[240:241], s[68:69] op_sel_hi:[1,1,0]
	v_pk_fma_f32 v[238:239], v[246:247], v[238:239], s[70:71] op_sel_hi:[1,1,0]
	v_pk_fma_f32 v[240:241], v[248:249], v[240:241], s[70:71] op_sel_hi:[1,1,0]
	v_pk_mul_f32 v[238:239], v[246:247], v[238:239]
	v_pk_mul_f32 v[240:241], v[248:249], v[240:241]
	v_pk_mul_f32 v[238:239], v[250:251], v[238:239]
	v_pk_mul_f32 v[240:241], v[252:253], v[240:241]
;     __device__ __forceinline__ void operator()(const f32x4 (&acc)[2][2][4][2], const Unit& u, int wr, int wc, int fr, int fq) const {
;     ...
;                 for (int bj = 0; bj < 2; ++bj) {
;                     const int oc = (bj ? FF : 0) + 128 * u.pn + 32 * wc + 8 * fq + 4 * n;
;                     const int cgc = 256 * u.pn + 128 * bj + 32 * wc + 8 * fq + 4 * n;
;                     const f32x4 cw0 = *(const f32x4*)(convw + oc), cw1 = *(const f32x4*)(convw + FF2 + oc), cw2 = *(const f32x4*)(convw + 2 * FF2 + oc), cb = *(const f32x4*)(convb + oc);
;                     f32x4 v[4];
; #pragma unroll
;                     for (int m = 0; m < 4; ++m) v[m] = acc[ai][bj][m][n] * rs[m];
;                     f32x4 hv = (f32x4){0.f, 0.f, 0.f, 0.f};
;                     if (!samp) {
;                         if ((blk & 31) != 0 && fr >= 14) hv = *(const f32x4*)(HALO + (size_t)(2 * blk + fr - 14) * FF2 + cgc);
;                         if ((u.pm & 7) == 7 && ai == 1 && wr == 1 && fr >= 14) *(f32x4*)(ncp + (size_t)((u.pm >> 3) * 2 + (fr - 14)) * FF2 + oc) = v[3];
;                     }
; #pragma unroll
;                     for (int m = 0; m < 4; ++m) {
;                         f32x4 cv;
;                         if (!samp) {
;                             const f32x4 prev = m ? v[m - 1] : hv;
; #pragma unroll
;                             for (int e = 0; e < 4; ++e) {
;                                 const int vi = __float_as_int(v[m][e]), pi = __float_as_int(prev[e]);
;                                 const int o1 = __builtin_amdgcn_mov_dpp(pi, 0x121, 0xf, 0xf, false);
;                                 const int o2 = __builtin_amdgcn_mov_dpp(pi, 0x122, 0xf, 0xf, false);
;                                 const float p1 = __int_as_float(__builtin_amdgcn_update_dpp(o1, vi, 0x111, 0xf, 0xf, false));
;                                 const float p2 = __int_as_float(__builtin_amdgcn_update_dpp(o2, vi, 0x112, 0xf, 0xf, false));
;                                 cv[e] = cb[e] + cw0[e] * p2 + cw1[e] * p1 + cw2[e] * v[m][e];
;                             }
;                         } else {
;                             const int ns = rowb + 16 * m + fr - MP;
;                             f32x4 s0 = (f32x4){0.f, 0.f, 0.f, 0.f}, s1 = s0;
;                             if (ns < NS) {
	v_max_f32_e32 v246, 0, v254
	v_max_f32_e32 v247, 0, v255
	v_max_f32_e32 v248, 0, v148
	v_max_f32_e32 v249, 0, v149
	v_fma_f32 v238, -|v254|, v238, v246
	v_fma_f32 v239, -|v255|, v239, v247
	v_fma_f32 v240, -|v148|, v240, v248
	v_fma_f32 v241, -|v149|, v241, v249
	v_pk_mul_f32 v[112:113], v[72:73], v[218:219] op_sel_hi:[1,0]
	v_pk_mul_f32 v[114:115], v[74:75], v[218:219] op_sel_hi:[1,0]
	v_pk_fma_f32 v[254:255], v[128:129], v[68:69], v[144:145]
	v_pk_fma_f32 v[148:149], v[130:131], v[70:71], v[146:147]
	v_fmac_f32_dpp v254, v68, v198 row_shr:1 row_mask:0xf bank_mask:0xf
	v_fmac_f32_dpp v255, v69, v199 row_shr:1 row_mask:0xf bank_mask:0xf
	v_fmac_f32_dpp v148, v70, v200 row_shr:1 row_mask:0xf bank_mask:0xf
	v_fmac_f32_dpp v149, v71, v201 row_shr:1 row_mask:0xf bank_mask:0xf
	v_fmac_f32_dpp v254, v68, v182 row_shr:2 row_mask:0xf bank_mask:0xf
	v_fmac_f32_dpp v255, v69, v183 row_shr:2 row_mask:0xf bank_mask:0xf
	v_fmac_f32_dpp v148, v70, v184 row_shr:2 row_mask:0xf bank_mask:0xf
	v_fmac_f32_dpp v149, v71, v185 row_shr:2 row_mask:0xf bank_mask:0xf
	v_fmac_f32_dpp v254, v112, v198 row_ror:1 row_mask:0xf bank_mask:0x1
	v_fmac_f32_dpp v255, v113, v199 row_ror:1 row_mask:0xf bank_mask:0x1
	v_fmac_f32_dpp v148, v114, v200 row_ror:1 row_mask:0xf bank_mask:0x1
	v_fmac_f32_dpp v149, v115, v201 row_ror:1 row_mask:0xf bank_mask:0x1
	v_fmac_f32_dpp v254, v112, v182 row_ror:2 row_mask:0xf bank_mask:0x1
	v_fmac_f32_dpp v255, v113, v183 row_ror:2 row_mask:0xf bank_mask:0x1
	v_fmac_f32_dpp v148, v114, v184 row_ror:2 row_mask:0xf bank_mask:0x1
	v_fmac_f32_dpp v149, v115, v185 row_ror:2 row_mask:0xf bank_mask:0x1
	v_pk_mul_f32 v[254:255], v[238:239], v[254:255]
	v_pk_mul_f32 v[148:149], v[240:241], v[148:149]
	v_cvt_pk_bf16_f32 v244, v254, v255
	v_cvt_pk_bf16_f32 v245, v148, v149
	s_add_u32 s56, s46, 0x2c000
	s_addc_u32 s57, s47, 0
	global_store_dwordx4 v151, v[242:245], s[56:57]
	v_mov_b32_e32 v220, 0
	v_mov_b32_e32 v221, 0
	v_mov_b32_e32 v222, 0
	v_mov_b32_e32 v223, 0
	v_mov_b32_e32 v116, 0
	v_mov_b32_e32 v117, 0
	v_mov_b32_e32 v118, 0
	v_mov_b32_e32 v119, 0
	v_mov_b32_e32 v84, 0
	v_mov_b32_e32 v85, 0
	v_mov_b32_e32 v86, 0
	v_mov_b32_e32 v87, 0
	v_mov_b32_e32 v100, 0
	v_mov_b32_e32 v101, 0
	v_mov_b32_e32 v102, 0
	v_mov_b32_e32 v103, 0
	v_mov_b32_e32 v68, 0
	v_mov_b32_e32 v69, 0
	v_mov_b32_e32 v70, 0
	v_mov_b32_e32 v71, 0
	s_and_b32 s14, s75, 31
	s_cselect_b64 s[92:93], -1, 0
	v_add_u32_e32 v246, 0x16000, v150
	s_and_b64 vcc, exec, s[86:87]
	s_cbranch_vccnz .Lfe_h0a
	s_mov_b64 s[14:15], exec
	s_mov_b64 exec, s[10:11]
	global_load_dwordx4 v[116:119], v246, s[44:45]
	global_load_dwordx4 v[84:87], v246, s[44:45] offset:16
	global_load_dwordx4 v[100:103], v246, s[44:45] offset:512
	global_load_dwordx4 v[68:71], v246, s[44:45] offset:528
	s_mov_b64 exec, s[14:15]
	s_and_b64 vcc, exec, s[92:93]
	s_cbranch_vccz .Lfe_h0a
	s_mov_b64 s[14:15], exec
	s_mov_b64 exec, s[10:11]
	global_load_dwordx4 v[220:223], v150, s[44:45]
	global_load_dwordx4 v[224:227], v150, s[44:45] offset:16
	global_load_dwordx4 v[228:231], v150, s[44:45] offset:512
	global_load_dwordx4 v[232:235], v150, s[44:45] offset:528
	s_mov_b64 exec, s[14:15]
.Lfe_h0a:
	s_mov_b32 s56, 0x3f07dc22
	v_pk_mul_f32 v[112:113], v[124:125], v[218:219] op_sel_hi:[1,0]
	v_pk_mul_f32 v[114:115], v[126:127], v[218:219] op_sel_hi:[1,0]
	v_pk_fma_f32 v[254:255], v[202:203], v[120:121], v[132:133]
	v_pk_fma_f32 v[148:149], v[204:205], v[122:123], v[134:135]
	v_fmac_f32_dpp v254, v120, v186 row_shr:1 row_mask:0xf bank_mask:0xf
	v_fmac_f32_dpp v255, v121, v187 row_shr:1 row_mask:0xf bank_mask:0xf
	v_fmac_f32_dpp v148, v122, v188 row_shr:1 row_mask:0xf bank_mask:0xf
	v_fmac_f32_dpp v149, v123, v189 row_shr:1 row_mask:0xf bank_mask:0xf
	v_fmac_f32_dpp v254, v120, v170 row_shr:2 row_mask:0xf bank_mask:0xf
	v_fmac_f32_dpp v255, v121, v171 row_shr:2 row_mask:0xf bank_mask:0xf
	v_fmac_f32_dpp v148, v122, v172 row_shr:2 row_mask:0xf bank_mask:0xf
	v_fmac_f32_dpp v149, v123, v173 row_shr:2 row_mask:0xf bank_mask:0xf
	v_fmac_f32_dpp v254, v112, v186 row_ror:1 row_mask:0xf bank_mask:0x1
	v_fmac_f32_dpp v255, v113, v187 row_ror:1 row_mask:0xf bank_mask:0x1
	v_fmac_f32_dpp v148, v114, v188 row_ror:1 row_mask:0xf bank_mask:0x1
	v_fmac_f32_dpp v149, v115, v189 row_ror:1 row_mask:0xf bank_mask:0x1
	v_fmac_f32_dpp v254, v112, v170 row_ror:2 row_mask:0xf bank_mask:0x1
	v_fmac_f32_dpp v255, v113, v171 row_ror:2 row_mask:0xf bank_mask:0x1
	v_fmac_f32_dpp v148, v114, v172 row_ror:2 row_mask:0xf bank_mask:0x1
	v_fmac_f32_dpp v149, v115, v173 row_ror:2 row_mask:0xf bank_mask:0x1
	v_fma_f32 v246, |v254|, s38, 1.0
	v_fma_f32 v247, |v255|, s38, 1.0
	v_fma_f32 v248, |v148|, s38, 1.0
	v_fma_f32 v249, |v149|, s38, 1.0
	v_pk_mul_f32 v[250:251], v[254:255], v[254:255]
	v_pk_mul_f32 v[252:253], v[148:149], v[148:149]
	v_rcp_f32_e32 v246, v246
	v_rcp_f32_e32 v247, v247
	v_rcp_f32_e32 v248, v248
	v_rcp_f32_e32 v249, v249
	v_pk_mul_f32 v[250:251], v[250:251], s[72:73] op_sel_hi:[1,0]
	v_pk_mul_f32 v[252:253], v[252:253], s[72:73] op_sel_hi:[1,0]
	v_exp_f32_e32 v250, v250
	v_exp_f32_e32 v251, v251
	v_exp_f32_e32 v252, v252
	v_exp_f32_e32 v253, v253
	v_pk_fma_f32 v[238:239], v[246:247], s[56:57], v[218:219] op_sel:[0,0,1] op_sel_hi:[1,0,1]
	v_pk_fma_f32 v[240:241], v[248:249], s[56:57], v[218:219] op_sel:[0,0,1] op_sel_hi:[1,0,1]
	v_pk_fma_f32 v[238:239], v[246:247], v[238:239], s[66:67] op_sel_hi:[1,1,0]
	v_pk_fma_f32 v[240:241], v[248:249], v[240:241], s[66:67] op_sel_hi:[1,1,0]
	v_pk_fma_f32 v[238:239], v[246:247], v[238:239], s[68:69] op_sel_hi:[1,1,0]
	v_pk_fma_f32 v[240:241], v[248:249], v[240:241], s[68:69] op_sel_hi:[1,1,0]
; __device__ __forceinline__ f32x2 gelu_pk(f32x2 v) {
;     const f32x2 av = __builtin_elementwise_abs(v), d = av * 0.2316418882f + 1.0f;
;     f32x2 t; t.x = __builtin_amdgcn_rcpf(d.x); t.y = __builtin_amdgcn_rcpf(d.y);
;     __device__ __forceinline__ void operator()(const f32x4 (&acc)[2][2][4][2], const Unit& u, int wr, int wc, int fr, int fq) const {
;     ...
;                     for (int m = 0; m < 4; ++m) {
;                         f32x4 cv;
;                         if (!samp) {
;                             const f32x4 prev = m ? v[m - 1] : hv;
; #pragma unroll
;                             for (int e = 0; e < 4; ++e) {
;                                 const int vi = __float_as_int(v[m][e]), pi = __float_as_int(prev[e]);
;                                 const int o1 = __builtin_amdgcn_mov_dpp(pi, 0x121, 0xf, 0xf, false);
;                                 const int o2 = __builtin_amdgcn_mov_dpp(pi, 0x122, 0xf, 0xf, false);
;                                 const float p1 = __int_as_float(__builtin_amdgcn_update_dpp(o1, vi, 0x111, 0xf, 0xf, false));
;                                 const float p2 = __int_as_float(__builtin_amdgcn_update_dpp(o2, vi, 0x112, 0xf, 0xf, false));
;                                 cv[e] = cb[e] + cw0[e] * p2 + cw1[e] * p1 + cw2[e] * v[m][e];
;                             }
;                         } else {
;                             const int ns = rowb + 16 * m + fr - MP;
;                             f32x4 s0 = (f32x4){0.f, 0.f, 0.f, 0.f}, s1 = s0;
;                             if (ns < NS) {
;                                 s0 = *(const f32x4*)(state + (size_t)(ns * 2 + 0) * FF2 + oc); s1 = *(const f32x4*)(state + (size_t)(ns * 2 + 1) * FF2 + oc);
;                                 *(f32x4*)(ncs + (size_t)(ns * 2 + 0) * FF2 + oc) = s1; *(f32x4*)(ncs + (size_t)(ns * 2 + 1) * FF2 + oc) = v[m];
;                             }
;                             cv = cb + cw0 * s0 + cw1 * s1 + cw2 * v[m];
;                         }
;                         if (bj == 0) cg[m] = gelu4(cv);
;                         else {
;                             const f32x4 r = cg[m] * cv;
;                             v2u w; w.x = cvt_pk_bf16(r[0], r[1]); w.y = cvt_pk_bf16(r[2], r[3]);
;                             *(v2u*)(ACT + (size_t)(rowb + 16 * m + fr) * FF + 128 * u.pn + 32 * wc + 8 * fq + 4 * n) = w;
;                         }
	v_pk_fma_f32 v[238:239], v[246:247], v[238:239], s[70:71] op_sel_hi:[1,1,0]
	v_pk_fma_f32 v[240:241], v[248:249], v[240:241], s[70:71] op_sel_hi:[1,1,0]
	v_pk_mul_f32 v[238:239], v[246:247], v[238:239]
	v_pk_mul_f32 v[240:241], v[248:249], v[240:241]
	v_pk_mul_f32 v[238:239], v[250:251], v[238:239]
	v_pk_mul_f32 v[240:241], v[252:253], v[240:241]
	v_max_f32_e32 v246, 0, v254
	v_max_f32_e32 v247, 0, v255
	v_max_f32_e32 v248, 0, v148
	v_max_f32_e32 v249, 0, v149
	v_fma_f32 v238, -|v254|, v238, v246
	v_fma_f32 v239, -|v255|, v239, v247
	v_fma_f32 v240, -|v148|, v240, v248
	v_fma_f32 v241, -|v149|, v241, v249
	v_pk_mul_f32 v[112:113], v[108:109], v[218:219] op_sel_hi:[1,0]
	v_pk_mul_f32 v[114:115], v[110:111], v[218:219] op_sel_hi:[1,0]
	v_pk_fma_f32 v[254:255], v[210:211], v[104:105], v[140:141]
	v_pk_fma_f32 v[148:149], v[212:213], v[106:107], v[142:143]
	v_fmac_f32_dpp v254, v104, v194 row_shr:1 row_mask:0xf bank_mask:0xf
	v_fmac_f32_dpp v255, v105, v195 row_shr:1 row_mask:0xf bank_mask:0xf
	v_fmac_f32_dpp v148, v106, v196 row_shr:1 row_mask:0xf bank_mask:0xf
	v_fmac_f32_dpp v149, v107, v197 row_shr:1 row_mask:0xf bank_mask:0xf
	v_fmac_f32_dpp v254, v104, v178 row_shr:2 row_mask:0xf bank_mask:0xf
	v_fmac_f32_dpp v255, v105, v179 row_shr:2 row_mask:0xf bank_mask:0xf
	v_fmac_f32_dpp v148, v106, v180 row_shr:2 row_mask:0xf bank_mask:0xf
	v_fmac_f32_dpp v149, v107, v181 row_shr:2 row_mask:0xf bank_mask:0xf
	v_fmac_f32_dpp v254, v112, v194 row_ror:1 row_mask:0xf bank_mask:0x1
	v_fmac_f32_dpp v255, v113, v195 row_ror:1 row_mask:0xf bank_mask:0x1
	v_fmac_f32_dpp v148, v114, v196 row_ror:1 row_mask:0xf bank_mask:0x1
	v_fmac_f32_dpp v149, v115, v197 row_ror:1 row_mask:0xf bank_mask:0x1
	v_fmac_f32_dpp v254, v112, v178 row_ror:2 row_mask:0xf bank_mask:0x1
	v_fmac_f32_dpp v255, v113, v179 row_ror:2 row_mask:0xf bank_mask:0x1
	v_fmac_f32_dpp v148, v114, v180 row_ror:2 row_mask:0xf bank_mask:0x1
	v_fmac_f32_dpp v149, v115, v181 row_ror:2 row_mask:0xf bank_mask:0x1
	v_pk_mul_f32 v[254:255], v[238:239], v[254:255]
	v_pk_mul_f32 v[148:149], v[240:241], v[148:149]
	v_cvt_pk_bf16_f32 v242, v254, v255
	v_cvt_pk_bf16_f32 v243, v148, v149
	v_pk_mul_f32 v[112:113], v[92:93], v[218:219] op_sel_hi:[1,0]
	v_pk_mul_f32 v[114:115], v[94:95], v[218:219] op_sel_hi:[1,0]
	v_pk_fma_f32 v[254:255], v[206:207], v[88:89], v[136:137]
	v_pk_fma_f32 v[148:149], v[208:209], v[90:91], v[138:139]
	v_fmac_f32_dpp v254, v88, v190 row_shr:1 row_mask:0xf bank_mask:0xf
	v_fmac_f32_dpp v255, v89, v191 row_shr:1 row_mask:0xf bank_mask:0xf
	v_fmac_f32_dpp v148, v90, v192 row_shr:1 row_mask:0xf bank_mask:0xf
	v_fmac_f32_dpp v149, v91, v193 row_shr:1 row_mask:0xf bank_mask:0xf
	v_fmac_f32_dpp v254, v88, v174 row_shr:2 row_mask:0xf bank_mask:0xf
	v_fmac_f32_dpp v255, v89, v175 row_shr:2 row_mask:0xf bank_mask:0xf
	v_fmac_f32_dpp v148, v90, v176 row_shr:2 row_mask:0xf bank_mask:0xf
	v_fmac_f32_dpp v149, v91, v177 row_shr:2 row_mask:0xf bank_mask:0xf
	v_fmac_f32_dpp v254, v112, v190 row_ror:1 row_mask:0xf bank_mask:0x1
	v_fmac_f32_dpp v255, v113, v191 row_ror:1 row_mask:0xf bank_mask:0x1
	v_fmac_f32_dpp v148, v114, v192 row_ror:1 row_mask:0xf bank_mask:0x1
	v_fmac_f32_dpp v149, v115, v193 row_ror:1 row_mask:0xf bank_mask:0x1
	v_fmac_f32_dpp v254, v112, v174 row_ror:2 row_mask:0xf bank_mask:0x1
	v_fmac_f32_dpp v255, v113, v175 row_ror:2 row_mask:0xf bank_mask:0x1
	v_fmac_f32_dpp v148, v114, v176 row_ror:2 row_mask:0xf bank_mask:0x1
	v_fmac_f32_dpp v149, v115, v177 row_ror:2 row_mask:0xf bank_mask:0x1
	v_fma_f32 v246, |v254|, s38, 1.0
	v_fma_f32 v247, |v255|, s38, 1.0
	v_fma_f32 v248, |v148|, s38, 1.0
	v_fma_f32 v249, |v149|, s38, 1.0
	v_pk_mul_f32 v[250:251], v[254:255], v[254:255]
	v_pk_mul_f32 v[252:253], v[148:149], v[148:149]
	v_rcp_f32_e32 v246, v246
	v_rcp_f32_e32 v247, v247
	v_rcp_f32_e32 v248, v248
	v_rcp_f32_e32 v249, v249
	v_pk_mul_f32 v[250:251], v[250:251], s[72:73] op_sel_hi:[1,0]
	v_pk_mul_f32 v[252:253], v[252:253], s[72:73] op_sel_hi:[1,0]
	v_exp_f32_e32 v250, v250
	v_exp_f32_e32 v251, v251
	v_exp_f32_e32 v252, v252
	v_exp_f32_e32 v253, v253
	v_pk_fma_f32 v[238:239], v[246:247], s[56:57], v[218:219] op_sel:[0,0,1] op_sel_hi:[1,0,1]
	v_pk_fma_f32 v[240:241], v[248:249], s[56:57], v[218:219] op_sel:[0,0,1] op_sel_hi:[1,0,1]
	v_pk_fma_f32 v[238:239], v[246:247], v[238:239], s[66:67] op_sel_hi:[1,1,0]
	v_pk_fma_f32 v[240:241], v[248:249], v[240:241], s[66:67] op_sel_hi:[1,1,0]
	v_pk_fma_f32 v[238:239], v[246:247], v[238:239], s[68:69] op_sel_hi:[1,1,0]
	v_pk_fma_f32 v[240:241], v[248:249], v[240:241], s[68:69] op_sel_hi:[1,1,0]
	v_pk_fma_f32 v[238:239], v[246:247], v[238:239], s[70:71] op_sel_hi:[1,1,0]
	v_pk_fma_f32 v[240:241], v[248:249], v[240:241], s[70:71] op_sel_hi:[1,1,0]
	v_pk_mul_f32 v[238:239], v[246:247], v[238:239]
	v_pk_mul_f32 v[240:241], v[248:249], v[240:241]
	v_pk_mul_f32 v[238:239], v[250:251], v[238:239]
	v_pk_mul_f32 v[240:241], v[252:253], v[240:241]
	v_max_f32_e32 v246, 0, v254
	v_max_f32_e32 v247, 0, v255
	v_max_f32_e32 v248, 0, v148
	v_max_f32_e32 v249, 0, v149
	v_fma_f32 v238, -|v254|, v238, v246
	v_fma_f32 v239, -|v255|, v239, v247
	v_fma_f32 v240, -|v148|, v240, v248
	v_fma_f32 v241, -|v149|, v241, v249
	v_pk_mul_f32 v[112:113], v[76:77], v[218:219] op_sel_hi:[1,0]
	v_pk_mul_f32 v[114:115], v[78:79], v[218:219] op_sel_hi:[1,0]
	v_pk_fma_f32 v[254:255], v[128:129], v[72:73], v[144:145]
	v_pk_fma_f32 v[148:149], v[130:131], v[74:75], v[146:147]
	v_fmac_f32_dpp v254, v72, v198 row_shr:1 row_mask:0xf bank_mask:0xf
	v_fmac_f32_dpp v255, v73, v199 row_shr:1 row_mask:0xf bank_mask:0xf
	v_fmac_f32_dpp v148, v74, v200 row_shr:1 row_mask:0xf bank_mask:0xf
; __device__ __forceinline__ f32x2 gelu_pk(f32x2 v) {
;     const f32x2 av = __builtin_elementwise_abs(v), d = av * 0.2316418882f + 1.0f;
;     f32x2 t; t.x = __builtin_amdgcn_rcpf(d.x); t.y = __builtin_amdgcn_rcpf(d.y);
;     __device__ __forceinline__ void operator()(const f32x4 (&acc)[2][2][4][2], const Unit& u, int wr, int wc, int fr, int fq) const {
;     ...
;                     for (int m = 0; m < 4; ++m) {
;                         f32x4 cv;
;                         if (!samp) {
;                             const f32x4 prev = m ? v[m - 1] : hv;
; #pragma unroll
;                             for (int e = 0; e < 4; ++e) {
;                                 const int vi = __float_as_int(v[m][e]), pi = __float_as_int(prev[e]);
;                                 const int o1 = __builtin_amdgcn_mov_dpp(pi, 0x121, 0xf, 0xf, false);
;                                 const int o2 = __builtin_amdgcn_mov_dpp(pi, 0x122, 0xf, 0xf, false);
;                                 const float p1 = __int_as_float(__builtin_amdgcn_update_dpp(o1, vi, 0x111, 0xf, 0xf, false));
;                                 const float p2 = __int_as_float(__builtin_amdgcn_update_dpp(o2, vi, 0x112, 0xf, 0xf, false));
;                                 cv[e] = cb[e] + cw0[e] * p2 + cw1[e] * p1 + cw2[e] * v[m][e];
;                             }
;                         } else {
;                             const int ns = rowb + 16 * m + fr - MP;
;                             f32x4 s0 = (f32x4){0.f, 0.f, 0.f, 0.f}, s1 = s0;
;                             if (ns < NS) {
;                                 s0 = *(const f32x4*)(state + (size_t)(ns * 2 + 0) * FF2 + oc); s1 = *(const f32x4*)(state + (size_t)(ns * 2 + 1) * FF2 + oc);
;                                 *(f32x4*)(ncs + (size_t)(ns * 2 + 0) * FF2 + oc) = s1; *(f32x4*)(ncs + (size_t)(ns * 2 + 1) * FF2 + oc) = v[m];
;                             }
;                             cv = cb + cw0 * s0 + cw1 * s1 + cw2 * v[m];
;                         }
;                         if (bj == 0) cg[m] = gelu4(cv);
;                         else {
;                             const f32x4 r = cg[m] * cv;
;                             v2u w; w.x = cvt_pk_bf16(r[0], r[1]); w.y = cvt_pk_bf16(r[2], r[3]);
;                             *(v2u*)(ACT + (size_t)(rowb + 16 * m + fr) * FF + 128 * u.pn + 32 * wc + 8 * fq + 4 * n) = w;
;                         }
	v_fmac_f32_dpp v149, v75, v201 row_shr:1 row_mask:0xf bank_mask:0xf
	v_fmac_f32_dpp v254, v72, v182 row_shr:2 row_mask:0xf bank_mask:0xf
	v_fmac_f32_dpp v255, v73, v183 row_shr:2 row_mask:0xf bank_mask:0xf
	v_fmac_f32_dpp v148, v74, v184 row_shr:2 row_mask:0xf bank_mask:0xf
	v_fmac_f32_dpp v149, v75, v185 row_shr:2 row_mask:0xf bank_mask:0xf
	v_fmac_f32_dpp v254, v112, v198 row_ror:1 row_mask:0xf bank_mask:0x1
	v_fmac_f32_dpp v255, v113, v199 row_ror:1 row_mask:0xf bank_mask:0x1
	v_fmac_f32_dpp v148, v114, v200 row_ror:1 row_mask:0xf bank_mask:0x1
	v_fmac_f32_dpp v149, v115, v201 row_ror:1 row_mask:0xf bank_mask:0x1
	v_fmac_f32_dpp v254, v112, v182 row_ror:2 row_mask:0xf bank_mask:0x1
	v_fmac_f32_dpp v255, v113, v183 row_ror:2 row_mask:0xf bank_mask:0x1
	v_fmac_f32_dpp v148, v114, v184 row_ror:2 row_mask:0xf bank_mask:0x1
	v_fmac_f32_dpp v149, v115, v185 row_ror:2 row_mask:0xf bank_mask:0x1
	v_pk_mul_f32 v[254:255], v[238:239], v[254:255]
	v_pk_mul_f32 v[148:149], v[240:241], v[148:149]
	v_cvt_pk_bf16_f32 v244, v254, v255
	v_cvt_pk_bf16_f32 v245, v148, v149
	s_add_u32 s56, s46, 0x16000
	s_addc_u32 s57, s47, 0
	global_store_dwordx4 v151, v[242:245], s[56:57]
	s_mov_b32 s56, 0x3f07dc22
	v_pk_mul_f32 v[112:113], v[48:49], v[218:219] op_sel_hi:[1,0]
	v_pk_mul_f32 v[114:115], v[50:51], v[218:219] op_sel_hi:[1,0]
	v_pk_fma_f32 v[254:255], v[202:203], v[56:57], v[132:133]
	v_pk_fma_f32 v[148:149], v[204:205], v[58:59], v[134:135]
	v_fmac_f32_dpp v254, v56, v186 row_shr:1 row_mask:0xf bank_mask:0xf
	v_fmac_f32_dpp v255, v57, v187 row_shr:1 row_mask:0xf bank_mask:0xf
	v_fmac_f32_dpp v148, v58, v188 row_shr:1 row_mask:0xf bank_mask:0xf
	v_fmac_f32_dpp v149, v59, v189 row_shr:1 row_mask:0xf bank_mask:0xf
	v_fmac_f32_dpp v254, v56, v170 row_shr:2 row_mask:0xf bank_mask:0xf
	v_fmac_f32_dpp v255, v57, v171 row_shr:2 row_mask:0xf bank_mask:0xf
	v_fmac_f32_dpp v148, v58, v172 row_shr:2 row_mask:0xf bank_mask:0xf
	v_fmac_f32_dpp v149, v59, v173 row_shr:2 row_mask:0xf bank_mask:0xf
	v_fmac_f32_dpp v254, v112, v186 row_ror:1 row_mask:0xf bank_mask:0x1
	v_fmac_f32_dpp v255, v113, v187 row_ror:1 row_mask:0xf bank_mask:0x1
	v_fmac_f32_dpp v148, v114, v188 row_ror:1 row_mask:0xf bank_mask:0x1
	v_fmac_f32_dpp v149, v115, v189 row_ror:1 row_mask:0xf bank_mask:0x1
	v_fmac_f32_dpp v254, v112, v170 row_ror:2 row_mask:0xf bank_mask:0x1
	v_fmac_f32_dpp v255, v113, v171 row_ror:2 row_mask:0xf bank_mask:0x1
	v_fmac_f32_dpp v148, v114, v172 row_ror:2 row_mask:0xf bank_mask:0x1
	v_fmac_f32_dpp v149, v115, v173 row_ror:2 row_mask:0xf bank_mask:0x1
	v_fma_f32 v246, |v254|, s38, 1.0
	v_fma_f32 v247, |v255|, s38, 1.0
	v_fma_f32 v248, |v148|, s38, 1.0
	v_fma_f32 v249, |v149|, s38, 1.0
	v_pk_mul_f32 v[250:251], v[254:255], v[254:255]
	v_pk_mul_f32 v[252:253], v[148:149], v[148:149]
	v_rcp_f32_e32 v246, v246
	v_rcp_f32_e32 v247, v247
	v_rcp_f32_e32 v248, v248
	v_rcp_f32_e32 v249, v249
	v_pk_mul_f32 v[250:251], v[250:251], s[72:73] op_sel_hi:[1,0]
	v_pk_mul_f32 v[252:253], v[252:253], s[72:73] op_sel_hi:[1,0]
	v_exp_f32_e32 v250, v250
	v_exp_f32_e32 v251, v251
	v_exp_f32_e32 v252, v252
	v_exp_f32_e32 v253, v253
	v_pk_fma_f32 v[238:239], v[246:247], s[56:57], v[218:219] op_sel:[0,0,1] op_sel_hi:[1,0,1]
	v_pk_fma_f32 v[240:241], v[248:249], s[56:57], v[218:219] op_sel:[0,0,1] op_sel_hi:[1,0,1]
	v_pk_fma_f32 v[238:239], v[246:247], v[238:239], s[66:67] op_sel_hi:[1,1,0]
	v_pk_fma_f32 v[240:241], v[248:249], v[240:241], s[66:67] op_sel_hi:[1,1,0]
	v_pk_fma_f32 v[238:239], v[246:247], v[238:239], s[68:69] op_sel_hi:[1,1,0]
	v_pk_fma_f32 v[240:241], v[248:249], v[240:241], s[68:69] op_sel_hi:[1,1,0]
	v_pk_fma_f32 v[238:239], v[246:247], v[238:239], s[70:71] op_sel_hi:[1,1,0]
	v_pk_fma_f32 v[240:241], v[248:249], v[240:241], s[70:71] op_sel_hi:[1,1,0]
	v_pk_mul_f32 v[238:239], v[246:247], v[238:239]
	v_pk_mul_f32 v[240:241], v[248:249], v[240:241]
	v_pk_mul_f32 v[238:239], v[250:251], v[238:239]
	v_pk_mul_f32 v[240:241], v[252:253], v[240:241]
	v_max_f32_e32 v246, 0, v254
	v_max_f32_e32 v247, 0, v255
	v_max_f32_e32 v248, 0, v148
	v_max_f32_e32 v249, 0, v149
	v_fma_f32 v238, -|v254|, v238, v246
	v_fma_f32 v239, -|v255|, v239, v247
	v_fma_f32 v240, -|v148|, v240, v248
	v_fma_f32 v241, -|v149|, v241, v249
	v_pk_mul_f32 v[112:113], v[32:33], v[218:219] op_sel_hi:[1,0]
	v_pk_mul_f32 v[114:115], v[34:35], v[218:219] op_sel_hi:[1,0]
	v_pk_fma_f32 v[254:255], v[210:211], v[40:41], v[140:141]
	v_pk_fma_f32 v[148:149], v[212:213], v[42:43], v[142:143]
	v_fmac_f32_dpp v254, v40, v194 row_shr:1 row_mask:0xf bank_mask:0xf
	v_fmac_f32_dpp v255, v41, v195 row_shr:1 row_mask:0xf bank_mask:0xf
	v_fmac_f32_dpp v148, v42, v196 row_shr:1 row_mask:0xf bank_mask:0xf
	v_fmac_f32_dpp v149, v43, v197 row_shr:1 row_mask:0xf bank_mask:0xf
	v_fmac_f32_dpp v254, v40, v178 row_shr:2 row_mask:0xf bank_mask:0xf
	v_fmac_f32_dpp v255, v41, v179 row_shr:2 row_mask:0xf bank_mask:0xf
	v_fmac_f32_dpp v148, v42, v180 row_shr:2 row_mask:0xf bank_mask:0xf
	v_fmac_f32_dpp v149, v43, v181 row_shr:2 row_mask:0xf bank_mask:0xf
	v_fmac_f32_dpp v254, v112, v194 row_ror:1 row_mask:0xf bank_mask:0x1
	v_fmac_f32_dpp v255, v113, v195 row_ror:1 row_mask:0xf bank_mask:0x1
	v_fmac_f32_dpp v148, v114, v196 row_ror:1 row_mask:0xf bank_mask:0x1
	v_fmac_f32_dpp v149, v115, v197 row_ror:1 row_mask:0xf bank_mask:0x1
	v_fmac_f32_dpp v254, v112, v178 row_ror:2 row_mask:0xf bank_mask:0x1
	v_fmac_f32_dpp v255, v113, v179 row_ror:2 row_mask:0xf bank_mask:0x1
	v_fmac_f32_dpp v148, v114, v180 row_ror:2 row_mask:0xf bank_mask:0x1
	v_fmac_f32_dpp v149, v115, v181 row_ror:2 row_mask:0xf bank_mask:0x1
	v_pk_mul_f32 v[254:255], v[238:239], v[254:255]
; __device__ __forceinline__ f32x2 gelu_pk(f32x2 v) {
;     const f32x2 av = __builtin_elementwise_abs(v), d = av * 0.2316418882f + 1.0f;
;     f32x2 t; t.x = __builtin_amdgcn_rcpf(d.x); t.y = __builtin_amdgcn_rcpf(d.y);
;     __device__ __forceinline__ void operator()(const f32x4 (&acc)[2][2][4][2], const Unit& u, int wr, int wc, int fr, int fq) const {
;     ...
;                     for (int m = 0; m < 4; ++m) {
;                         f32x4 cv;
;                         if (!samp) {
;                             const f32x4 prev = m ? v[m - 1] : hv;
; #pragma unroll
;                             for (int e = 0; e < 4; ++e) {
;                                 const int vi = __float_as_int(v[m][e]), pi = __float_as_int(prev[e]);
;                                 const int o1 = __builtin_amdgcn_mov_dpp(pi, 0x121, 0xf, 0xf, false);
;                                 const int o2 = __builtin_amdgcn_mov_dpp(pi, 0x122, 0xf, 0xf, false);
;                                 const float p1 = __int_as_float(__builtin_amdgcn_update_dpp(o1, vi, 0x111, 0xf, 0xf, false));
;                                 const float p2 = __int_as_float(__builtin_amdgcn_update_dpp(o2, vi, 0x112, 0xf, 0xf, false));
;                                 cv[e] = cb[e] + cw0[e] * p2 + cw1[e] * p1 + cw2[e] * v[m][e];
;                             }
;                         } else {
;                             const int ns = rowb + 16 * m + fr - MP;
;                             f32x4 s0 = (f32x4){0.f, 0.f, 0.f, 0.f}, s1 = s0;
;                             if (ns < NS) {
;                                 s0 = *(const f32x4*)(state + (size_t)(ns * 2 + 0) * FF2 + oc); s1 = *(const f32x4*)(state + (size_t)(ns * 2 + 1) * FF2 + oc);
;                                 *(f32x4*)(ncs + (size_t)(ns * 2 + 0) * FF2 + oc) = s1; *(f32x4*)(ncs + (size_t)(ns * 2 + 1) * FF2 + oc) = v[m];
;                             }
;                             cv = cb + cw0 * s0 + cw1 * s1 + cw2 * v[m];
;                         }
;                         if (bj == 0) cg[m] = gelu4(cv);
;                         else {
;                             const f32x4 r = cg[m] * cv;
;                             v2u w; w.x = cvt_pk_bf16(r[0], r[1]); w.y = cvt_pk_bf16(r[2], r[3]);
;                             *(v2u*)(ACT + (size_t)(rowb + 16 * m + fr) * FF + 128 * u.pn + 32 * wc + 8 * fq + 4 * n) = w;
;                         }
	v_pk_mul_f32 v[148:149], v[240:241], v[148:149]
	v_cvt_pk_bf16_f32 v242, v254, v255
	v_cvt_pk_bf16_f32 v243, v148, v149
	v_pk_mul_f32 v[112:113], v[16:17], v[218:219] op_sel_hi:[1,0]
	v_pk_mul_f32 v[114:115], v[18:19], v[218:219] op_sel_hi:[1,0]
	v_pk_fma_f32 v[254:255], v[206:207], v[24:25], v[136:137]
	v_pk_fma_f32 v[148:149], v[208:209], v[26:27], v[138:139]
	v_fmac_f32_dpp v254, v24, v190 row_shr:1 row_mask:0xf bank_mask:0xf
	v_fmac_f32_dpp v255, v25, v191 row_shr:1 row_mask:0xf bank_mask:0xf
	v_fmac_f32_dpp v148, v26, v192 row_shr:1 row_mask:0xf bank_mask:0xf
	v_fmac_f32_dpp v149, v27, v193 row_shr:1 row_mask:0xf bank_mask:0xf
	v_fmac_f32_dpp v254, v24, v174 row_shr:2 row_mask:0xf bank_mask:0xf
	v_fmac_f32_dpp v255, v25, v175 row_shr:2 row_mask:0xf bank_mask:0xf
	v_fmac_f32_dpp v148, v26, v176 row_shr:2 row_mask:0xf bank_mask:0xf
	v_fmac_f32_dpp v149, v27, v177 row_shr:2 row_mask:0xf bank_mask:0xf
	v_fmac_f32_dpp v254, v112, v190 row_ror:1 row_mask:0xf bank_mask:0x1
	v_fmac_f32_dpp v255, v113, v191 row_ror:1 row_mask:0xf bank_mask:0x1
	v_fmac_f32_dpp v148, v114, v192 row_ror:1 row_mask:0xf bank_mask:0x1
	v_fmac_f32_dpp v149, v115, v193 row_ror:1 row_mask:0xf bank_mask:0x1
	v_fmac_f32_dpp v254, v112, v174 row_ror:2 row_mask:0xf bank_mask:0x1
	v_fmac_f32_dpp v255, v113, v175 row_ror:2 row_mask:0xf bank_mask:0x1
	v_fmac_f32_dpp v148, v114, v176 row_ror:2 row_mask:0xf bank_mask:0x1
	v_fmac_f32_dpp v149, v115, v177 row_ror:2 row_mask:0xf bank_mask:0x1
	v_fma_f32 v246, |v254|, s38, 1.0
	v_fma_f32 v247, |v255|, s38, 1.0
	v_fma_f32 v248, |v148|, s38, 1.0
	v_fma_f32 v249, |v149|, s38, 1.0
	v_pk_mul_f32 v[250:251], v[254:255], v[254:255]
	v_pk_mul_f32 v[252:253], v[148:149], v[148:149]
	v_rcp_f32_e32 v246, v246
	v_rcp_f32_e32 v247, v247
	v_rcp_f32_e32 v248, v248
	v_rcp_f32_e32 v249, v249
	v_pk_mul_f32 v[250:251], v[250:251], s[72:73] op_sel_hi:[1,0]
	v_pk_mul_f32 v[252:253], v[252:253], s[72:73] op_sel_hi:[1,0]
	v_exp_f32_e32 v250, v250
	v_exp_f32_e32 v251, v251
	v_exp_f32_e32 v252, v252
	v_exp_f32_e32 v253, v253
	v_pk_fma_f32 v[238:239], v[246:247], s[56:57], v[218:219] op_sel:[0,0,1] op_sel_hi:[1,0,1]
	v_pk_fma_f32 v[240:241], v[248:249], s[56:57], v[218:219] op_sel:[0,0,1] op_sel_hi:[1,0,1]
	v_pk_fma_f32 v[238:239], v[246:247], v[238:239], s[66:67] op_sel_hi:[1,1,0]
	v_pk_fma_f32 v[240:241], v[248:249], v[240:241], s[66:67] op_sel_hi:[1,1,0]
	v_pk_fma_f32 v[238:239], v[246:247], v[238:239], s[68:69] op_sel_hi:[1,1,0]
	v_pk_fma_f32 v[240:241], v[248:249], v[240:241], s[68:69] op_sel_hi:[1,1,0]
	v_pk_fma_f32 v[238:239], v[246:247], v[238:239], s[70:71] op_sel_hi:[1,1,0]
	v_pk_fma_f32 v[240:241], v[248:249], v[240:241], s[70:71] op_sel_hi:[1,1,0]
	v_pk_mul_f32 v[238:239], v[246:247], v[238:239]
	v_pk_mul_f32 v[240:241], v[248:249], v[240:241]
	v_pk_mul_f32 v[238:239], v[250:251], v[238:239]
	v_pk_mul_f32 v[240:241], v[252:253], v[240:241]
	v_max_f32_e32 v246, 0, v254
	v_max_f32_e32 v247, 0, v255
	v_max_f32_e32 v248, 0, v148
	v_max_f32_e32 v249, 0, v149
	v_fma_f32 v238, -|v254|, v238, v246
	v_fma_f32 v239, -|v255|, v239, v247
	v_fma_f32 v240, -|v148|, v240, v248
	v_fma_f32 v241, -|v149|, v241, v249
	v_pk_mul_f32 v[112:113], v[0:1], v[218:219] op_sel_hi:[1,0]
	v_pk_mul_f32 v[114:115], v[2:3], v[218:219] op_sel_hi:[1,0]
	v_pk_fma_f32 v[254:255], v[128:129], v[8:9], v[144:145]
	v_pk_fma_f32 v[148:149], v[130:131], v[10:11], v[146:147]
	v_fmac_f32_dpp v254, v8, v198 row_shr:1 row_mask:0xf bank_mask:0xf
	v_fmac_f32_dpp v255, v9, v199 row_shr:1 row_mask:0xf bank_mask:0xf
	v_fmac_f32_dpp v148, v10, v200 row_shr:1 row_mask:0xf bank_mask:0xf
	v_fmac_f32_dpp v149, v11, v201 row_shr:1 row_mask:0xf bank_mask:0xf
	v_fmac_f32_dpp v254, v8, v182 row_shr:2 row_mask:0xf bank_mask:0xf
	v_fmac_f32_dpp v255, v9, v183 row_shr:2 row_mask:0xf bank_mask:0xf
	v_fmac_f32_dpp v148, v10, v184 row_shr:2 row_mask:0xf bank_mask:0xf
	v_fmac_f32_dpp v149, v11, v185 row_shr:2 row_mask:0xf bank_mask:0xf
	v_fmac_f32_dpp v254, v112, v198 row_ror:1 row_mask:0xf bank_mask:0x1
	v_fmac_f32_dpp v255, v113, v199 row_ror:1 row_mask:0xf bank_mask:0x1
	v_fmac_f32_dpp v148, v114, v200 row_ror:1 row_mask:0xf bank_mask:0x1
	v_fmac_f32_dpp v149, v115, v201 row_ror:1 row_mask:0xf bank_mask:0x1
	v_fmac_f32_dpp v254, v112, v182 row_ror:2 row_mask:0xf bank_mask:0x1
	v_fmac_f32_dpp v255, v113, v183 row_ror:2 row_mask:0xf bank_mask:0x1
	v_fmac_f32_dpp v148, v114, v184 row_ror:2 row_mask:0xf bank_mask:0x1
	v_fmac_f32_dpp v149, v115, v185 row_ror:2 row_mask:0xf bank_mask:0x1
	v_pk_mul_f32 v[254:255], v[238:239], v[254:255]
	v_pk_mul_f32 v[148:149], v[240:241], v[148:149]
	v_cvt_pk_bf16_f32 v244, v254, v255
	v_cvt_pk_bf16_f32 v245, v148, v149
	s_add_u32 s56, s46, 0xf2000
	s_addc_u32 s57, s47, 0
	global_store_dwordx4 v151, v[242:245], s[56:57]
	s_mov_b32 s56, 0x3f07dc22
	v_pk_mul_f32 v[112:113], v[52:53], v[218:219] op_sel_hi:[1,0]
	v_pk_mul_f32 v[114:115], v[54:55], v[218:219] op_sel_hi:[1,0]
	v_pk_fma_f32 v[254:255], v[202:203], v[48:49], v[132:133]
	v_pk_fma_f32 v[148:149], v[204:205], v[50:51], v[134:135]
	v_fmac_f32_dpp v254, v48, v186 row_shr:1 row_mask:0xf bank_mask:0xf
	v_fmac_f32_dpp v255, v49, v187 row_shr:1 row_mask:0xf bank_mask:0xf
	v_fmac_f32_dpp v148, v50, v188 row_shr:1 row_mask:0xf bank_mask:0xf
	v_fmac_f32_dpp v149, v51, v189 row_shr:1 row_mask:0xf bank_mask:0xf
	v_fmac_f32_dpp v254, v48, v170 row_shr:2 row_mask:0xf bank_mask:0xf
	v_fmac_f32_dpp v255, v49, v171 row_shr:2 row_mask:0xf bank_mask:0xf
	v_fmac_f32_dpp v148, v50, v172 row_shr:2 row_mask:0xf bank_mask:0xf
	v_fmac_f32_dpp v149, v51, v173 row_shr:2 row_mask:0xf bank_mask:0xf
	v_fmac_f32_dpp v254, v112, v186 row_ror:1 row_mask:0xf bank_mask:0x1
; __device__ __forceinline__ f32x2 gelu_pk(f32x2 v) {
;     const f32x2 av = __builtin_elementwise_abs(v), d = av * 0.2316418882f + 1.0f;
;     __device__ __forceinline__ void operator()(const f32x4 (&acc)[2][2][4][2], const Unit& u, int wr, int wc, int fr, int fq) const {
;     ...
; #pragma unroll
;                     for (int m = 0; m < 4; ++m) {
;                         f32x4 cv;
;                         if (!samp) {
;                             const f32x4 prev = m ? v[m - 1] : hv;
; #pragma unroll
;                             for (int e = 0; e < 4; ++e) {
;                                 const int vi = __float_as_int(v[m][e]), pi = __float_as_int(prev[e]);
;                                 const int o1 = __builtin_amdgcn_mov_dpp(pi, 0x121, 0xf, 0xf, false);
;                                 const int o2 = __builtin_amdgcn_mov_dpp(pi, 0x122, 0xf, 0xf, false);
;                                 const float p1 = __int_as_float(__builtin_amdgcn_update_dpp(o1, vi, 0x111, 0xf, 0xf, false));
;                                 const float p2 = __int_as_float(__builtin_amdgcn_update_dpp(o2, vi, 0x112, 0xf, 0xf, false));
;                                 cv[e] = cb[e] + cw0[e] * p2 + cw1[e] * p1 + cw2[e] * v[m][e];
;                             }
;                         } else {
;                             const int ns = rowb + 16 * m + fr - MP;
;                             f32x4 s0 = (f32x4){0.f, 0.f, 0.f, 0.f}, s1 = s0;
;                             if (ns < NS) {
;                                 s0 = *(const f32x4*)(state + (size_t)(ns * 2 + 0) * FF2 + oc); s1 = *(const f32x4*)(state + (size_t)(ns * 2 + 1) * FF2 + oc);
;                                 *(f32x4*)(ncs + (size_t)(ns * 2 + 0) * FF2 + oc) = s1; *(f32x4*)(ncs + (size_t)(ns * 2 + 1) * FF2 + oc) = v[m];
;                             }
;                             cv = cb + cw0 * s0 + cw1 * s1 + cw2 * v[m];
;                         }
;                         if (bj == 0) cg[m] = gelu4(cv);
;                         else {
;                             const f32x4 r = cg[m] * cv;
;                             v2u w; w.x = cvt_pk_bf16(r[0], r[1]); w.y = cvt_pk_bf16(r[2], r[3]);
;                             *(v2u*)(ACT + (size_t)(rowb + 16 * m + fr) * FF + 128 * u.pn + 32 * wc + 8 * fq + 4 * n) = w;
;                         }
	v_fmac_f32_dpp v255, v113, v187 row_ror:1 row_mask:0xf bank_mask:0x1
	v_fmac_f32_dpp v148, v114, v188 row_ror:1 row_mask:0xf bank_mask:0x1
	v_fmac_f32_dpp v149, v115, v189 row_ror:1 row_mask:0xf bank_mask:0x1
	v_fmac_f32_dpp v254, v112, v170 row_ror:2 row_mask:0xf bank_mask:0x1
	v_fmac_f32_dpp v255, v113, v171 row_ror:2 row_mask:0xf bank_mask:0x1
	v_fmac_f32_dpp v148, v114, v172 row_ror:2 row_mask:0xf bank_mask:0x1
	v_fmac_f32_dpp v149, v115, v173 row_ror:2 row_mask:0xf bank_mask:0x1
	v_fma_f32 v246, |v254|, s38, 1.0
	v_fma_f32 v247, |v255|, s38, 1.0
	v_fma_f32 v248, |v148|, s38, 1.0
	v_fma_f32 v249, |v149|, s38, 1.0
	v_pk_mul_f32 v[250:251], v[254:255], v[254:255]
	v_pk_mul_f32 v[252:253], v[148:149], v[148:149]
	v_rcp_f32_e32 v246, v246
	v_rcp_f32_e32 v247, v247
	v_rcp_f32_e32 v248, v248
	v_rcp_f32_e32 v249, v249
	v_pk_mul_f32 v[250:251], v[250:251], s[72:73] op_sel_hi:[1,0]
	v_pk_mul_f32 v[252:253], v[252:253], s[72:73] op_sel_hi:[1,0]
	v_exp_f32_e32 v250, v250
	v_exp_f32_e32 v251, v251
	v_exp_f32_e32 v252, v252
	v_exp_f32_e32 v253, v253
	v_pk_fma_f32 v[238:239], v[246:247], s[56:57], v[218:219] op_sel:[0,0,1] op_sel_hi:[1,0,1]
	v_pk_fma_f32 v[240:241], v[248:249], s[56:57], v[218:219] op_sel:[0,0,1] op_sel_hi:[1,0,1]
	v_pk_fma_f32 v[238:239], v[246:247], v[238:239], s[66:67] op_sel_hi:[1,1,0]
	v_pk_fma_f32 v[240:241], v[248:249], v[240:241], s[66:67] op_sel_hi:[1,1,0]
	v_pk_fma_f32 v[238:239], v[246:247], v[238:239], s[68:69] op_sel_hi:[1,1,0]
	v_pk_fma_f32 v[240:241], v[248:249], v[240:241], s[68:69] op_sel_hi:[1,1,0]
	v_pk_fma_f32 v[238:239], v[246:247], v[238:239], s[70:71] op_sel_hi:[1,1,0]
	v_pk_fma_f32 v[240:241], v[248:249], v[240:241], s[70:71] op_sel_hi:[1,1,0]
	v_pk_mul_f32 v[238:239], v[246:247], v[238:239]
	v_pk_mul_f32 v[240:241], v[248:249], v[240:241]
	v_pk_mul_f32 v[238:239], v[250:251], v[238:239]
	v_pk_mul_f32 v[240:241], v[252:253], v[240:241]
	v_max_f32_e32 v246, 0, v254
	v_max_f32_e32 v247, 0, v255
	v_max_f32_e32 v248, 0, v148
	v_max_f32_e32 v249, 0, v149
	v_fma_f32 v238, -|v254|, v238, v246
	v_fma_f32 v239, -|v255|, v239, v247
	v_fma_f32 v240, -|v148|, v240, v248
	v_fma_f32 v241, -|v149|, v241, v249
	v_pk_mul_f32 v[112:113], v[36:37], v[218:219] op_sel_hi:[1,0]
	v_pk_mul_f32 v[114:115], v[38:39], v[218:219] op_sel_hi:[1,0]
	v_pk_fma_f32 v[254:255], v[210:211], v[32:33], v[140:141]
	v_pk_fma_f32 v[148:149], v[212:213], v[34:35], v[142:143]
	v_fmac_f32_dpp v254, v32, v194 row_shr:1 row_mask:0xf bank_mask:0xf
	v_fmac_f32_dpp v255, v33, v195 row_shr:1 row_mask:0xf bank_mask:0xf
	v_fmac_f32_dpp v148, v34, v196 row_shr:1 row_mask:0xf bank_mask:0xf
	v_fmac_f32_dpp v149, v35, v197 row_shr:1 row_mask:0xf bank_mask:0xf
	v_fmac_f32_dpp v254, v32, v178 row_shr:2 row_mask:0xf bank_mask:0xf
	v_fmac_f32_dpp v255, v33, v179 row_shr:2 row_mask:0xf bank_mask:0xf
	v_fmac_f32_dpp v148, v34, v180 row_shr:2 row_mask:0xf bank_mask:0xf
	v_fmac_f32_dpp v149, v35, v181 row_shr:2 row_mask:0xf bank_mask:0xf
	v_fmac_f32_dpp v254, v112, v194 row_ror:1 row_mask:0xf bank_mask:0x1
	v_fmac_f32_dpp v255, v113, v195 row_ror:1 row_mask:0xf bank_mask:0x1
	v_fmac_f32_dpp v148, v114, v196 row_ror:1 row_mask:0xf bank_mask:0x1
	v_fmac_f32_dpp v149, v115, v197 row_ror:1 row_mask:0xf bank_mask:0x1
	v_fmac_f32_dpp v254, v112, v178 row_ror:2 row_mask:0xf bank_mask:0x1
	v_fmac_f32_dpp v255, v113, v179 row_ror:2 row_mask:0xf bank_mask:0x1
	v_fmac_f32_dpp v148, v114, v180 row_ror:2 row_mask:0xf bank_mask:0x1
	v_fmac_f32_dpp v149, v115, v181 row_ror:2 row_mask:0xf bank_mask:0x1
	v_pk_mul_f32 v[254:255], v[238:239], v[254:255]
	v_pk_mul_f32 v[148:149], v[240:241], v[148:149]
	v_cvt_pk_bf16_f32 v242, v254, v255
	v_cvt_pk_bf16_f32 v243, v148, v149
	v_pk_mul_f32 v[112:113], v[20:21], v[218:219] op_sel_hi:[1,0]
	v_pk_mul_f32 v[114:115], v[22:23], v[218:219] op_sel_hi:[1,0]
	v_pk_fma_f32 v[254:255], v[206:207], v[16:17], v[136:137]
	v_pk_fma_f32 v[148:149], v[208:209], v[18:19], v[138:139]
	v_fmac_f32_dpp v254, v16, v190 row_shr:1 row_mask:0xf bank_mask:0xf
	v_fmac_f32_dpp v255, v17, v191 row_shr:1 row_mask:0xf bank_mask:0xf
	v_fmac_f32_dpp v148, v18, v192 row_shr:1 row_mask:0xf bank_mask:0xf
	v_fmac_f32_dpp v149, v19, v193 row_shr:1 row_mask:0xf bank_mask:0xf
	v_fmac_f32_dpp v254, v16, v174 row_shr:2 row_mask:0xf bank_mask:0xf
	v_fmac_f32_dpp v255, v17, v175 row_shr:2 row_mask:0xf bank_mask:0xf
	v_fmac_f32_dpp v148, v18, v176 row_shr:2 row_mask:0xf bank_mask:0xf
	v_fmac_f32_dpp v149, v19, v177 row_shr:2 row_mask:0xf bank_mask:0xf
	v_fmac_f32_dpp v254, v112, v190 row_ror:1 row_mask:0xf bank_mask:0x1
	v_fmac_f32_dpp v255, v113, v191 row_ror:1 row_mask:0xf bank_mask:0x1
	v_fmac_f32_dpp v148, v114, v192 row_ror:1 row_mask:0xf bank_mask:0x1
	v_fmac_f32_dpp v149, v115, v193 row_ror:1 row_mask:0xf bank_mask:0x1
	v_fmac_f32_dpp v254, v112, v174 row_ror:2 row_mask:0xf bank_mask:0x1
	v_fmac_f32_dpp v255, v113, v175 row_ror:2 row_mask:0xf bank_mask:0x1
	v_fmac_f32_dpp v148, v114, v176 row_ror:2 row_mask:0xf bank_mask:0x1
	v_fmac_f32_dpp v149, v115, v177 row_ror:2 row_mask:0xf bank_mask:0x1
	v_fma_f32 v246, |v254|, s38, 1.0
	v_fma_f32 v247, |v255|, s38, 1.0
	v_fma_f32 v248, |v148|, s38, 1.0
	v_fma_f32 v249, |v149|, s38, 1.0
	v_pk_mul_f32 v[250:251], v[254:255], v[254:255]
	v_pk_mul_f32 v[252:253], v[148:149], v[148:149]
	v_rcp_f32_e32 v246, v246
	v_rcp_f32_e32 v247, v247
	v_rcp_f32_e32 v248, v248
	v_rcp_f32_e32 v249, v249
	v_pk_mul_f32 v[250:251], v[250:251], s[72:73] op_sel_hi:[1,0]
	v_pk_mul_f32 v[252:253], v[252:253], s[72:73] op_sel_hi:[1,0]
	v_exp_f32_e32 v250, v250
	v_exp_f32_e32 v251, v251
	v_exp_f32_e32 v252, v252
	v_exp_f32_e32 v253, v253
; __device__ __forceinline__ f32x2 gelu_pk(f32x2 v) {
;     const f32x2 av = __builtin_elementwise_abs(v), d = av * 0.2316418882f + 1.0f;
;     __device__ __forceinline__ void operator()(const f32x4 (&acc)[2][2][4][2], const Unit& u, int wr, int wc, int fr, int fq) const {
;     ...
; #pragma unroll
;                     for (int m = 0; m < 4; ++m) {
;                         f32x4 cv;
;                         if (!samp) {
;                             const f32x4 prev = m ? v[m - 1] : hv;
; #pragma unroll
;                             for (int e = 0; e < 4; ++e) {
;                                 const int vi = __float_as_int(v[m][e]), pi = __float_as_int(prev[e]);
;                                 const int o1 = __builtin_amdgcn_mov_dpp(pi, 0x121, 0xf, 0xf, false);
;                                 const int o2 = __builtin_amdgcn_mov_dpp(pi, 0x122, 0xf, 0xf, false);
;                                 const float p1 = __int_as_float(__builtin_amdgcn_update_dpp(o1, vi, 0x111, 0xf, 0xf, false));
;                                 const float p2 = __int_as_float(__builtin_amdgcn_update_dpp(o2, vi, 0x112, 0xf, 0xf, false));
;                                 cv[e] = cb[e] + cw0[e] * p2 + cw1[e] * p1 + cw2[e] * v[m][e];
;                             }
;                         } else {
;                             const int ns = rowb + 16 * m + fr - MP;
;                             f32x4 s0 = (f32x4){0.f, 0.f, 0.f, 0.f}, s1 = s0;
;                             if (ns < NS) {
;                                 s0 = *(const f32x4*)(state + (size_t)(ns * 2 + 0) * FF2 + oc); s1 = *(const f32x4*)(state + (size_t)(ns * 2 + 1) * FF2 + oc);
;                                 *(f32x4*)(ncs + (size_t)(ns * 2 + 0) * FF2 + oc) = s1; *(f32x4*)(ncs + (size_t)(ns * 2 + 1) * FF2 + oc) = v[m];
;                             }
;                             cv = cb + cw0 * s0 + cw1 * s1 + cw2 * v[m];
;                         }
;                         if (bj == 0) cg[m] = gelu4(cv);
;                         else {
;                             const f32x4 r = cg[m] * cv;
;                             v2u w; w.x = cvt_pk_bf16(r[0], r[1]); w.y = cvt_pk_bf16(r[2], r[3]);
;                             *(v2u*)(ACT + (size_t)(rowb + 16 * m + fr) * FF + 128 * u.pn + 32 * wc + 8 * fq + 4 * n) = w;
;                         }
	v_pk_fma_f32 v[238:239], v[246:247], s[56:57], v[218:219] op_sel:[0,0,1] op_sel_hi:[1,0,1]
	v_pk_fma_f32 v[240:241], v[248:249], s[56:57], v[218:219] op_sel:[0,0,1] op_sel_hi:[1,0,1]
	v_pk_fma_f32 v[238:239], v[246:247], v[238:239], s[66:67] op_sel_hi:[1,1,0]
	v_pk_fma_f32 v[240:241], v[248:249], v[240:241], s[66:67] op_sel_hi:[1,1,0]
	v_pk_fma_f32 v[238:239], v[246:247], v[238:239], s[68:69] op_sel_hi:[1,1,0]
	v_pk_fma_f32 v[240:241], v[248:249], v[240:241], s[68:69] op_sel_hi:[1,1,0]
	v_pk_fma_f32 v[238:239], v[246:247], v[238:239], s[70:71] op_sel_hi:[1,1,0]
	v_pk_fma_f32 v[240:241], v[248:249], v[240:241], s[70:71] op_sel_hi:[1,1,0]
	v_pk_mul_f32 v[238:239], v[246:247], v[238:239]
	v_pk_mul_f32 v[240:241], v[248:249], v[240:241]
	v_pk_mul_f32 v[238:239], v[250:251], v[238:239]
	v_pk_mul_f32 v[240:241], v[252:253], v[240:241]
	v_max_f32_e32 v246, 0, v254
	v_max_f32_e32 v247, 0, v255
	v_max_f32_e32 v248, 0, v148
	v_max_f32_e32 v249, 0, v149
	v_fma_f32 v238, -|v254|, v238, v246
	v_fma_f32 v239, -|v255|, v239, v247
	v_fma_f32 v240, -|v148|, v240, v248
	v_fma_f32 v241, -|v149|, v241, v249
	v_pk_mul_f32 v[112:113], v[4:5], v[218:219] op_sel_hi:[1,0]
	v_pk_mul_f32 v[114:115], v[6:7], v[218:219] op_sel_hi:[1,0]
	v_pk_fma_f32 v[254:255], v[128:129], v[0:1], v[144:145]
	v_pk_fma_f32 v[148:149], v[130:131], v[2:3], v[146:147]
	v_fmac_f32_dpp v254, v0, v198 row_shr:1 row_mask:0xf bank_mask:0xf
	v_fmac_f32_dpp v255, v1, v199 row_shr:1 row_mask:0xf bank_mask:0xf
	v_fmac_f32_dpp v148, v2, v200 row_shr:1 row_mask:0xf bank_mask:0xf
	v_fmac_f32_dpp v149, v3, v201 row_shr:1 row_mask:0xf bank_mask:0xf
	v_fmac_f32_dpp v254, v0, v182 row_shr:2 row_mask:0xf bank_mask:0xf
	v_fmac_f32_dpp v255, v1, v183 row_shr:2 row_mask:0xf bank_mask:0xf
	v_fmac_f32_dpp v148, v2, v184 row_shr:2 row_mask:0xf bank_mask:0xf
	v_fmac_f32_dpp v149, v3, v185 row_shr:2 row_mask:0xf bank_mask:0xf
	v_fmac_f32_dpp v254, v112, v198 row_ror:1 row_mask:0xf bank_mask:0x1
	v_fmac_f32_dpp v255, v113, v199 row_ror:1 row_mask:0xf bank_mask:0x1
	v_fmac_f32_dpp v148, v114, v200 row_ror:1 row_mask:0xf bank_mask:0x1
	v_fmac_f32_dpp v149, v115, v201 row_ror:1 row_mask:0xf bank_mask:0x1
	v_fmac_f32_dpp v254, v112, v182 row_ror:2 row_mask:0xf bank_mask:0x1
	v_fmac_f32_dpp v255, v113, v183 row_ror:2 row_mask:0xf bank_mask:0x1
	v_fmac_f32_dpp v148, v114, v184 row_ror:2 row_mask:0xf bank_mask:0x1
	v_fmac_f32_dpp v149, v115, v185 row_ror:2 row_mask:0xf bank_mask:0x1
	v_pk_mul_f32 v[254:255], v[238:239], v[254:255]
	v_pk_mul_f32 v[148:149], v[240:241], v[148:149]
	v_cvt_pk_bf16_f32 v244, v254, v255
	v_cvt_pk_bf16_f32 v245, v148, v149
	s_add_u32 s56, s46, 0xdc000
	s_addc_u32 s57, s47, 0
	global_store_dwordx4 v151, v[242:245], s[56:57]
	s_mov_b32 s56, 0x3f07dc22
	v_pk_mul_f32 v[112:113], v[60:61], v[218:219] op_sel_hi:[1,0]
	v_pk_mul_f32 v[114:115], v[62:63], v[218:219] op_sel_hi:[1,0]
	v_pk_fma_f32 v[254:255], v[202:203], v[52:53], v[132:133]
	v_pk_fma_f32 v[148:149], v[204:205], v[54:55], v[134:135]
	v_fmac_f32_dpp v254, v52, v186 row_shr:1 row_mask:0xf bank_mask:0xf
	v_fmac_f32_dpp v255, v53, v187 row_shr:1 row_mask:0xf bank_mask:0xf
	v_fmac_f32_dpp v148, v54, v188 row_shr:1 row_mask:0xf bank_mask:0xf
	v_fmac_f32_dpp v149, v55, v189 row_shr:1 row_mask:0xf bank_mask:0xf
	v_fmac_f32_dpp v254, v52, v170 row_shr:2 row_mask:0xf bank_mask:0xf
	v_fmac_f32_dpp v255, v53, v171 row_shr:2 row_mask:0xf bank_mask:0xf
	v_fmac_f32_dpp v148, v54, v172 row_shr:2 row_mask:0xf bank_mask:0xf
	v_fmac_f32_dpp v149, v55, v173 row_shr:2 row_mask:0xf bank_mask:0xf
	v_fmac_f32_dpp v254, v112, v186 row_ror:1 row_mask:0xf bank_mask:0x1
	v_fmac_f32_dpp v255, v113, v187 row_ror:1 row_mask:0xf bank_mask:0x1
	v_fmac_f32_dpp v148, v114, v188 row_ror:1 row_mask:0xf bank_mask:0x1
	v_fmac_f32_dpp v149, v115, v189 row_ror:1 row_mask:0xf bank_mask:0x1
	v_fmac_f32_dpp v254, v112, v170 row_ror:2 row_mask:0xf bank_mask:0x1
	v_fmac_f32_dpp v255, v113, v171 row_ror:2 row_mask:0xf bank_mask:0x1
	v_fmac_f32_dpp v148, v114, v172 row_ror:2 row_mask:0xf bank_mask:0x1
	v_fmac_f32_dpp v149, v115, v173 row_ror:2 row_mask:0xf bank_mask:0x1
	v_fma_f32 v246, |v254|, s38, 1.0
	v_fma_f32 v247, |v255|, s38, 1.0
	v_fma_f32 v248, |v148|, s38, 1.0
	v_fma_f32 v249, |v149|, s38, 1.0
	v_pk_mul_f32 v[250:251], v[254:255], v[254:255]
	v_pk_mul_f32 v[252:253], v[148:149], v[148:149]
	v_rcp_f32_e32 v246, v246
	v_rcp_f32_e32 v247, v247
	v_rcp_f32_e32 v248, v248
	v_rcp_f32_e32 v249, v249
	v_pk_mul_f32 v[250:251], v[250:251], s[72:73] op_sel_hi:[1,0]
	v_pk_mul_f32 v[252:253], v[252:253], s[72:73] op_sel_hi:[1,0]
	v_exp_f32_e32 v250, v250
	v_exp_f32_e32 v251, v251
	v_exp_f32_e32 v252, v252
	v_exp_f32_e32 v253, v253
	v_pk_fma_f32 v[238:239], v[246:247], s[56:57], v[218:219] op_sel:[0,0,1] op_sel_hi:[1,0,1]
	v_pk_fma_f32 v[240:241], v[248:249], s[56:57], v[218:219] op_sel:[0,0,1] op_sel_hi:[1,0,1]
	v_pk_fma_f32 v[238:239], v[246:247], v[238:239], s[66:67] op_sel_hi:[1,1,0]
	v_pk_fma_f32 v[240:241], v[248:249], v[240:241], s[66:67] op_sel_hi:[1,1,0]
	v_pk_fma_f32 v[238:239], v[246:247], v[238:239], s[68:69] op_sel_hi:[1,1,0]
	v_pk_fma_f32 v[240:241], v[248:249], v[240:241], s[68:69] op_sel_hi:[1,1,0]
	v_pk_fma_f32 v[238:239], v[246:247], v[238:239], s[70:71] op_sel_hi:[1,1,0]
	v_pk_fma_f32 v[240:241], v[248:249], v[240:241], s[70:71] op_sel_hi:[1,1,0]
	v_pk_mul_f32 v[238:239], v[246:247], v[238:239]
	v_pk_mul_f32 v[240:241], v[248:249], v[240:241]
	v_pk_mul_f32 v[238:239], v[250:251], v[238:239]
	v_pk_mul_f32 v[240:241], v[252:253], v[240:241]
	v_max_f32_e32 v246, 0, v254
	v_max_f32_e32 v247, 0, v255
	v_max_f32_e32 v248, 0, v148
	v_max_f32_e32 v249, 0, v149
; __device__ __forceinline__ f32x2 gelu_pk(f32x2 v) {
;     const f32x2 av = __builtin_elementwise_abs(v), d = av * 0.2316418882f + 1.0f;
;     __device__ __forceinline__ void operator()(const f32x4 (&acc)[2][2][4][2], const Unit& u, int wr, int wc, int fr, int fq) const {
;     ...
; #pragma unroll
;                     for (int m = 0; m < 4; ++m) {
;                         f32x4 cv;
;                         if (!samp) {
;                             const f32x4 prev = m ? v[m - 1] : hv;
; #pragma unroll
;                             for (int e = 0; e < 4; ++e) {
;                                 const int vi = __float_as_int(v[m][e]), pi = __float_as_int(prev[e]);
;                                 const int o1 = __builtin_amdgcn_mov_dpp(pi, 0x121, 0xf, 0xf, false);
;                                 const int o2 = __builtin_amdgcn_mov_dpp(pi, 0x122, 0xf, 0xf, false);
;                                 const float p1 = __int_as_float(__builtin_amdgcn_update_dpp(o1, vi, 0x111, 0xf, 0xf, false));
;                                 const float p2 = __int_as_float(__builtin_amdgcn_update_dpp(o2, vi, 0x112, 0xf, 0xf, false));
;                                 cv[e] = cb[e] + cw0[e] * p2 + cw1[e] * p1 + cw2[e] * v[m][e];
;                             }
;                         } else {
;                             const int ns = rowb + 16 * m + fr - MP;
;                             f32x4 s0 = (f32x4){0.f, 0.f, 0.f, 0.f}, s1 = s0;
;                             if (ns < NS) {
;                                 s0 = *(const f32x4*)(state + (size_t)(ns * 2 + 0) * FF2 + oc); s1 = *(const f32x4*)(state + (size_t)(ns * 2 + 1) * FF2 + oc);
;                                 *(f32x4*)(ncs + (size_t)(ns * 2 + 0) * FF2 + oc) = s1; *(f32x4*)(ncs + (size_t)(ns * 2 + 1) * FF2 + oc) = v[m];
;                             }
;                             cv = cb + cw0 * s0 + cw1 * s1 + cw2 * v[m];
;                         }
;                         if (bj == 0) cg[m] = gelu4(cv);
;                         else {
;                             const f32x4 r = cg[m] * cv;
;                             v2u w; w.x = cvt_pk_bf16(r[0], r[1]); w.y = cvt_pk_bf16(r[2], r[3]);
;                             *(v2u*)(ACT + (size_t)(rowb + 16 * m + fr) * FF + 128 * u.pn + 32 * wc + 8 * fq + 4 * n) = w;
;                         }
	v_fma_f32 v238, -|v254|, v238, v246
	v_fma_f32 v239, -|v255|, v239, v247
	v_fma_f32 v240, -|v148|, v240, v248
	v_fma_f32 v241, -|v149|, v241, v249
	v_pk_mul_f32 v[112:113], v[44:45], v[218:219] op_sel_hi:[1,0]
	v_pk_mul_f32 v[114:115], v[46:47], v[218:219] op_sel_hi:[1,0]
	v_pk_fma_f32 v[254:255], v[210:211], v[36:37], v[140:141]
	v_pk_fma_f32 v[148:149], v[212:213], v[38:39], v[142:143]
	v_fmac_f32_dpp v254, v36, v194 row_shr:1 row_mask:0xf bank_mask:0xf
	v_fmac_f32_dpp v255, v37, v195 row_shr:1 row_mask:0xf bank_mask:0xf
	v_fmac_f32_dpp v148, v38, v196 row_shr:1 row_mask:0xf bank_mask:0xf
	v_fmac_f32_dpp v149, v39, v197 row_shr:1 row_mask:0xf bank_mask:0xf
	v_fmac_f32_dpp v254, v36, v178 row_shr:2 row_mask:0xf bank_mask:0xf
	v_fmac_f32_dpp v255, v37, v179 row_shr:2 row_mask:0xf bank_mask:0xf
	v_fmac_f32_dpp v148, v38, v180 row_shr:2 row_mask:0xf bank_mask:0xf
	v_fmac_f32_dpp v149, v39, v181 row_shr:2 row_mask:0xf bank_mask:0xf
	v_fmac_f32_dpp v254, v112, v194 row_ror:1 row_mask:0xf bank_mask:0x1
	v_fmac_f32_dpp v255, v113, v195 row_ror:1 row_mask:0xf bank_mask:0x1
	v_fmac_f32_dpp v148, v114, v196 row_ror:1 row_mask:0xf bank_mask:0x1
	v_fmac_f32_dpp v149, v115, v197 row_ror:1 row_mask:0xf bank_mask:0x1
	v_fmac_f32_dpp v254, v112, v178 row_ror:2 row_mask:0xf bank_mask:0x1
	v_fmac_f32_dpp v255, v113, v179 row_ror:2 row_mask:0xf bank_mask:0x1
	v_fmac_f32_dpp v148, v114, v180 row_ror:2 row_mask:0xf bank_mask:0x1
	v_fmac_f32_dpp v149, v115, v181 row_ror:2 row_mask:0xf bank_mask:0x1
	v_pk_mul_f32 v[254:255], v[238:239], v[254:255]
	v_pk_mul_f32 v[148:149], v[240:241], v[148:149]
	v_cvt_pk_bf16_f32 v242, v254, v255
	v_cvt_pk_bf16_f32 v243, v148, v149
	v_pk_mul_f32 v[112:113], v[28:29], v[218:219] op_sel_hi:[1,0]
	v_pk_mul_f32 v[114:115], v[30:31], v[218:219] op_sel_hi:[1,0]
	v_pk_fma_f32 v[254:255], v[206:207], v[20:21], v[136:137]
	v_pk_fma_f32 v[148:149], v[208:209], v[22:23], v[138:139]
	v_fmac_f32_dpp v254, v20, v190 row_shr:1 row_mask:0xf bank_mask:0xf
	v_fmac_f32_dpp v255, v21, v191 row_shr:1 row_mask:0xf bank_mask:0xf
	v_fmac_f32_dpp v148, v22, v192 row_shr:1 row_mask:0xf bank_mask:0xf
	v_fmac_f32_dpp v149, v23, v193 row_shr:1 row_mask:0xf bank_mask:0xf
	v_fmac_f32_dpp v254, v20, v174 row_shr:2 row_mask:0xf bank_mask:0xf
	v_fmac_f32_dpp v255, v21, v175 row_shr:2 row_mask:0xf bank_mask:0xf
	v_fmac_f32_dpp v148, v22, v176 row_shr:2 row_mask:0xf bank_mask:0xf
	v_fmac_f32_dpp v149, v23, v177 row_shr:2 row_mask:0xf bank_mask:0xf
	v_fmac_f32_dpp v254, v112, v190 row_ror:1 row_mask:0xf bank_mask:0x1
	v_fmac_f32_dpp v255, v113, v191 row_ror:1 row_mask:0xf bank_mask:0x1
	v_fmac_f32_dpp v148, v114, v192 row_ror:1 row_mask:0xf bank_mask:0x1
	v_fmac_f32_dpp v149, v115, v193 row_ror:1 row_mask:0xf bank_mask:0x1
	v_fmac_f32_dpp v254, v112, v174 row_ror:2 row_mask:0xf bank_mask:0x1
	v_fmac_f32_dpp v255, v113, v175 row_ror:2 row_mask:0xf bank_mask:0x1
	v_fmac_f32_dpp v148, v114, v176 row_ror:2 row_mask:0xf bank_mask:0x1
	v_fmac_f32_dpp v149, v115, v177 row_ror:2 row_mask:0xf bank_mask:0x1
	v_fma_f32 v246, |v254|, s38, 1.0
	v_fma_f32 v247, |v255|, s38, 1.0
	v_fma_f32 v248, |v148|, s38, 1.0
	v_fma_f32 v249, |v149|, s38, 1.0
	v_pk_mul_f32 v[250:251], v[254:255], v[254:255]
	v_pk_mul_f32 v[252:253], v[148:149], v[148:149]
	v_rcp_f32_e32 v246, v246
	v_rcp_f32_e32 v247, v247
	v_rcp_f32_e32 v248, v248
	v_rcp_f32_e32 v249, v249
	v_pk_mul_f32 v[250:251], v[250:251], s[72:73] op_sel_hi:[1,0]
	v_pk_mul_f32 v[252:253], v[252:253], s[72:73] op_sel_hi:[1,0]
	v_exp_f32_e32 v250, v250
	v_exp_f32_e32 v251, v251
	v_exp_f32_e32 v252, v252
	v_exp_f32_e32 v253, v253
	v_pk_fma_f32 v[238:239], v[246:247], s[56:57], v[218:219] op_sel:[0,0,1] op_sel_hi:[1,0,1]
	v_pk_fma_f32 v[240:241], v[248:249], s[56:57], v[218:219] op_sel:[0,0,1] op_sel_hi:[1,0,1]
	v_pk_fma_f32 v[238:239], v[246:247], v[238:239], s[66:67] op_sel_hi:[1,1,0]
	v_pk_fma_f32 v[240:241], v[248:249], v[240:241], s[66:67] op_sel_hi:[1,1,0]
	v_pk_fma_f32 v[238:239], v[246:247], v[238:239], s[68:69] op_sel_hi:[1,1,0]
	v_pk_fma_f32 v[240:241], v[248:249], v[240:241], s[68:69] op_sel_hi:[1,1,0]
	v_pk_fma_f32 v[238:239], v[246:247], v[238:239], s[70:71] op_sel_hi:[1,1,0]
	v_pk_fma_f32 v[240:241], v[248:249], v[240:241], s[70:71] op_sel_hi:[1,1,0]
	v_pk_mul_f32 v[238:239], v[246:247], v[238:239]
	v_pk_mul_f32 v[240:241], v[248:249], v[240:241]
	v_pk_mul_f32 v[238:239], v[250:251], v[238:239]
	v_pk_mul_f32 v[240:241], v[252:253], v[240:241]
	v_max_f32_e32 v246, 0, v254
	v_max_f32_e32 v247, 0, v255
	v_max_f32_e32 v248, 0, v148
	v_max_f32_e32 v249, 0, v149
	v_fma_f32 v238, -|v254|, v238, v246
	v_fma_f32 v239, -|v255|, v239, v247
	v_fma_f32 v240, -|v148|, v240, v248
	v_fma_f32 v241, -|v149|, v241, v249
	v_pk_mul_f32 v[112:113], v[12:13], v[218:219] op_sel_hi:[1,0]
	v_pk_mul_f32 v[114:115], v[14:15], v[218:219] op_sel_hi:[1,0]
	v_pk_fma_f32 v[254:255], v[128:129], v[4:5], v[144:145]
	v_pk_fma_f32 v[148:149], v[130:131], v[6:7], v[146:147]
	v_fmac_f32_dpp v254, v4, v198 row_shr:1 row_mask:0xf bank_mask:0xf
	v_fmac_f32_dpp v255, v5, v199 row_shr:1 row_mask:0xf bank_mask:0xf
	v_fmac_f32_dpp v148, v6, v200 row_shr:1 row_mask:0xf bank_mask:0xf
	v_fmac_f32_dpp v149, v7, v201 row_shr:1 row_mask:0xf bank_mask:0xf
	v_fmac_f32_dpp v254, v4, v182 row_shr:2 row_mask:0xf bank_mask:0xf
	v_fmac_f32_dpp v255, v5, v183 row_shr:2 row_mask:0xf bank_mask:0xf
	v_fmac_f32_dpp v148, v6, v184 row_shr:2 row_mask:0xf bank_mask:0xf
	v_fmac_f32_dpp v149, v7, v185 row_shr:2 row_mask:0xf bank_mask:0xf
	v_fmac_f32_dpp v254, v112, v198 row_ror:1 row_mask:0xf bank_mask:0x1
	v_fmac_f32_dpp v255, v113, v199 row_ror:1 row_mask:0xf bank_mask:0x1
	v_fmac_f32_dpp v148, v114, v200 row_ror:1 row_mask:0xf bank_mask:0x1
	v_fmac_f32_dpp v149, v115, v201 row_ror:1 row_mask:0xf bank_mask:0x1
	v_fmac_f32_dpp v254, v112, v182 row_ror:2 row_mask:0xf bank_mask:0x1
	v_fmac_f32_dpp v255, v113, v183 row_ror:2 row_mask:0xf bank_mask:0x1
	v_fmac_f32_dpp v148, v114, v184 row_ror:2 row_mask:0xf bank_mask:0x1
	v_fmac_f32_dpp v149, v115, v185 row_ror:2 row_mask:0xf bank_mask:0x1
	v_pk_mul_f32 v[254:255], v[238:239], v[254:255]
	v_pk_mul_f32 v[148:149], v[240:241], v[148:149]
	v_cvt_pk_bf16_f32 v244, v254, v255
	v_cvt_pk_bf16_f32 v245, v148, v149
	s_add_u32 s56, s46, 0xc6000
	s_addc_u32 s57, s47, 0
	global_store_dwordx4 v151, v[242:245], s[56:57]
	s_and_b64 vcc, exec, s[86:87]
	s_cbranch_vccz .Lfe_h0b
	s_and_saveexec_b64 s[14:15], s[8:9]
	s_cbranch_execz .Lfe_hw3
	s_mov_b32 s13, 0x100001
	s_branch .Lfe_hw1

;     ...
;         if constexpr (!AFTER_DRAIN) { E(acc, cur, wr, wc, fr, fq); S.done(cur); }
;         if (!has_next) break;
; #pragma unroll
;         for (int a = 0; a < 2; ++a)
; #pragma unroll
;             for (int b = 0; b < 2; ++b)
; #pragma unroll
;                 for (int m = 0; m < 4; ++m)
; #pragma unroll
;                     for (int n = 0; n < 2; ++n) acc[a][b][m][n] = (f32x4){0.f, 0.f, 0.f, 0.f};
;         cur = nxt; cA = nA; cB = nB; ++ui;
.Lfe_done:
	v_mov_b32_e32 v218, 0x358637bd
	v_readlane_b32 s90, v236, 23
	v_readlane_b32 s91, v236, 24
	s_nop 3
	s_branch .LBB0_1114
